# GEMM K-loops: priority changes moved off the barrier-release-to-first-MFMA path; redundant lgkmcnt wait dropped
# speedup vs baseline: 1.0021x; 1.0021x over previous
.LBB0_217:
	s_add_u32 s36, s34, 0xfffc0080
	s_addc_u32 s37, s35, -1
	s_cmp_eq_u32 s71, 12
	s_cselect_b32 s39, s7, s37
	s_cselect_b32 s38, s25, s36
	s_cselect_b32 s37, s23, s70
	s_cselect_b32 s36, s68, s69
	v_lshl_add_u64 v[150:151], s[34:35], 0, v[138:139]
	s_add_i32 m0, s31, 0xc000
	s_nop 0
	global_load_lds_dwordx4 v[150:151], off
	v_lshl_add_u64 v[150:151], s[34:35], 0, v[140:141]
	s_add_i32 m0, s31, 0xe000
	s_nop 0
	global_load_lds_dwordx4 v[150:151], off
	ds_read_b128 v[146:149], v155
	ds_read_b128 v[158:161], v155 offset:1024
	ds_read_b128 v[162:165], v155 offset:2048
	ds_read_b128 v[166:169], v155 offset:3072
	ds_read_b128 v[170:173], v156
	ds_read_b128 v[174:177], v156 offset:1024
	ds_read_b128 v[178:181], v156 offset:2048
	ds_read_b128 v[182:185], v156 offset:3072
	ds_read_b128 v[186:189], v157
	ds_read_b128 v[190:193], v157 offset:1024
	ds_read_b128 v[194:197], v157 offset:2048
	ds_read_b128 v[198:201], v157 offset:3072
	ds_read_b128 v[202:205], v157 offset:4096
	ds_read_b128 v[206:209], v157 offset:5120
	ds_read_b128 v[210:213], v157 offset:6144
	ds_read_b128 v[214:217], v157 offset:7168
	s_waitcnt vmcnt(8)
	s_waitcnt lgkmcnt(0)
	s_setprio 1
	s_barrier
	v_mfma_f32_16x16x32_bf16 v[124:127], v[146:149], v[186:189], v[124:127]
	v_mfma_f32_16x16x32_bf16 v[120:123], v[162:165], v[186:189], v[120:123]
	v_mfma_f32_16x16x32_bf16 v[108:111], v[146:149], v[194:197], v[108:111]
	v_mfma_f32_16x16x32_bf16 v[104:107], v[162:165], v[194:197], v[104:107]
	v_mfma_f32_16x16x32_bf16 v[92:95], v[146:149], v[202:205], v[92:95]
	v_mfma_f32_16x16x32_bf16 v[88:91], v[162:165], v[202:205], v[88:91]
	v_mfma_f32_16x16x32_bf16 v[76:79], v[146:149], v[210:213], v[76:79]
	v_mfma_f32_16x16x32_bf16 v[72:75], v[162:165], v[210:213], v[72:75]
	v_mfma_f32_16x16x32_bf16 v[124:127], v[158:161], v[190:193], v[124:127]
	v_mfma_f32_16x16x32_bf16 v[120:123], v[166:169], v[190:193], v[120:123]
	v_mfma_f32_16x16x32_bf16 v[108:111], v[158:161], v[198:201], v[108:111]
	v_mfma_f32_16x16x32_bf16 v[104:107], v[166:169], v[198:201], v[104:107]
	v_mfma_f32_16x16x32_bf16 v[92:95], v[158:161], v[206:209], v[92:95]
	v_mfma_f32_16x16x32_bf16 v[88:91], v[166:169], v[206:209], v[88:91]
	v_mfma_f32_16x16x32_bf16 v[76:79], v[158:161], v[214:217], v[76:79]
	v_mfma_f32_16x16x32_bf16 v[72:75], v[166:169], v[214:217], v[72:75]
	s_setprio 0
	s_setprio 1
	v_mfma_f32_16x16x32_bf16 v[116:119], v[170:173], v[186:189], v[116:119]
	v_mfma_f32_16x16x32_bf16 v[112:115], v[178:181], v[186:189], v[112:115]
	v_mfma_f32_16x16x32_bf16 v[100:103], v[170:173], v[194:197], v[100:103]
	v_mfma_f32_16x16x32_bf16 v[96:99], v[178:181], v[194:197], v[96:99]
	v_mfma_f32_16x16x32_bf16 v[84:87], v[170:173], v[202:205], v[84:87]
	v_mfma_f32_16x16x32_bf16 v[80:83], v[178:181], v[202:205], v[80:83]
	v_mfma_f32_16x16x32_bf16 v[68:71], v[170:173], v[210:213], v[68:71]
	v_mfma_f32_16x16x32_bf16 v[64:67], v[178:181], v[210:213], v[64:67]
	v_mfma_f32_16x16x32_bf16 v[116:119], v[174:177], v[190:193], v[116:119]
	v_mfma_f32_16x16x32_bf16 v[112:115], v[182:185], v[190:193], v[112:115]
	v_mfma_f32_16x16x32_bf16 v[100:103], v[174:177], v[198:201], v[100:103]
	v_mfma_f32_16x16x32_bf16 v[96:99], v[182:185], v[198:201], v[96:99]
	v_mfma_f32_16x16x32_bf16 v[84:87], v[174:177], v[206:209], v[84:87]
	v_mfma_f32_16x16x32_bf16 v[80:83], v[182:185], v[206:209], v[80:83]
	v_mfma_f32_16x16x32_bf16 v[68:71], v[174:177], v[214:217], v[68:71]
	v_mfma_f32_16x16x32_bf16 v[64:67], v[182:185], v[214:217], v[64:67]
	s_barrier
	s_setprio 0
	s_add_i32 s72, s65, s43
	v_lshl_add_u64 v[150:151], s[36:37], 0, v[130:131]
	s_mov_b32 m0, s72
	s_nop 0
	global_load_lds_dwordx4 v[150:151], off
	s_add_i32 m0, s72, 0x2000
	s_add_u32 s72, s36, 0x40000
	v_lshl_add_u64 v[218:219], s[36:37], 0, v[134:135]
	s_addc_u32 s73, s37, 0
	s_add_i32 s74, s67, s43
	global_load_lds_dwordx4 v[218:219], off
	v_lshl_add_u64 v[220:221], s[72:73], 0, v[130:131]
	s_mov_b32 m0, s74
	v_lshl_add_u64 v[222:223], s[38:39], 0, v[132:133]
	global_load_lds_dwordx4 v[220:221], off
	v_lshl_add_u64 v[220:221], s[72:73], 0, v[134:135]
	s_add_i32 m0, s74, 0x2000
	s_nop 0
	global_load_lds_dwordx4 v[220:221], off
	v_lshl_add_u64 v[220:221], s[38:39], 0, v[128:129]
	s_mov_b32 m0, s31
	s_nop 0
	global_load_lds_dwordx4 v[220:221], off
	s_mov_b32 m0, s46
	s_nop 0
	global_load_lds_dwordx4 v[222:223], off
	ds_read_b128 v[186:189], v157 offset:16384
	ds_read_b128 v[190:193], v157 offset:17408
	ds_read_b128 v[194:197], v157 offset:18432
	ds_read_b128 v[198:201], v157 offset:19456
	ds_read_b128 v[202:205], v157 offset:20480
	ds_read_b128 v[206:209], v157 offset:21504
	ds_read_b128 v[210:213], v157 offset:22528
	ds_read_b128 v[214:217], v157 offset:23552
	s_waitcnt vmcnt(8)
	s_waitcnt lgkmcnt(0)
	s_setprio 1
	s_barrier
	v_mfma_f32_16x16x32_bf16 v[60:63], v[146:149], v[186:189], v[60:63]
	v_mfma_f32_16x16x32_bf16 v[56:59], v[162:165], v[186:189], v[56:59]
	v_mfma_f32_16x16x32_bf16 v[44:47], v[146:149], v[194:197], v[44:47]
	v_mfma_f32_16x16x32_bf16 v[40:43], v[162:165], v[194:197], v[40:43]
	v_mfma_f32_16x16x32_bf16 v[28:31], v[146:149], v[202:205], v[28:31]
	v_mfma_f32_16x16x32_bf16 v[24:27], v[162:165], v[202:205], v[24:27]
	v_mfma_f32_16x16x32_bf16 v[12:15], v[146:149], v[210:213], v[12:15]
	v_mfma_f32_16x16x32_bf16 v[8:11], v[162:165], v[210:213], v[8:11]
	v_mfma_f32_16x16x32_bf16 v[60:63], v[158:161], v[190:193], v[60:63]
	v_mfma_f32_16x16x32_bf16 v[56:59], v[166:169], v[190:193], v[56:59]
	v_mfma_f32_16x16x32_bf16 v[44:47], v[158:161], v[198:201], v[44:47]
	v_mfma_f32_16x16x32_bf16 v[40:43], v[166:169], v[198:201], v[40:43]
	v_mfma_f32_16x16x32_bf16 v[28:31], v[158:161], v[206:209], v[28:31]
	v_mfma_f32_16x16x32_bf16 v[24:27], v[166:169], v[206:209], v[24:27]
	v_mfma_f32_16x16x32_bf16 v[12:15], v[158:161], v[214:217], v[12:15]
	v_mfma_f32_16x16x32_bf16 v[8:11], v[166:169], v[214:217], v[8:11]
	s_setprio 0
	s_setprio 1
	v_mfma_f32_16x16x32_bf16 v[52:55], v[170:173], v[186:189], v[52:55]
	v_mfma_f32_16x16x32_bf16 v[48:51], v[178:181], v[186:189], v[48:51]
	v_mfma_f32_16x16x32_bf16 v[36:39], v[170:173], v[194:197], v[36:39]
	v_mfma_f32_16x16x32_bf16 v[32:35], v[178:181], v[194:197], v[32:35]
	v_mfma_f32_16x16x32_bf16 v[20:23], v[170:173], v[202:205], v[20:23]
	v_mfma_f32_16x16x32_bf16 v[16:19], v[178:181], v[202:205], v[16:19]
	v_mfma_f32_16x16x32_bf16 v[4:7], v[170:173], v[210:213], v[4:7]
	v_mfma_f32_16x16x32_bf16 v[0:3], v[178:181], v[210:213], v[0:3]
	v_mfma_f32_16x16x32_bf16 v[52:55], v[174:177], v[190:193], v[52:55]
	v_mfma_f32_16x16x32_bf16 v[48:51], v[182:185], v[190:193], v[48:51]
	v_mfma_f32_16x16x32_bf16 v[36:39], v[174:177], v[198:201], v[36:39]
	v_mfma_f32_16x16x32_bf16 v[32:35], v[182:185], v[198:201], v[32:35]
	v_mfma_f32_16x16x32_bf16 v[20:23], v[174:177], v[206:209], v[20:23]
	v_mfma_f32_16x16x32_bf16 v[16:19], v[182:185], v[206:209], v[16:19]
	v_mfma_f32_16x16x32_bf16 v[4:7], v[174:177], v[214:217], v[4:7]
	v_mfma_f32_16x16x32_bf16 v[0:3], v[182:185], v[214:217], v[0:3]
	s_barrier
	s_setprio 0
	s_add_i32 s72, 0, 0x18000
	s_add_i32 s73, 0, 0x1c000
	s_add_u32 s38, s38, 0x40000
	s_addc_u32 s39, s39, 0
	s_mov_b32 m0, s47
	v_lshl_add_u64 v[224:225], s[38:39], 0, v[128:129]
	global_load_lds_dwordx4 v[224:225], off
	v_lshl_add_u64 v[224:225], s[38:39], 0, v[132:133]
	s_mov_b32 m0, s48
	s_nop 0
	global_load_lds_dwordx4 v[224:225], off
	v_add_u32_e32 v136, s72, v153
	ds_read_b128 v[146:149], v136
	ds_read_b128 v[158:161], v136 offset:1024
	ds_read_b128 v[162:165], v136 offset:2048
	ds_read_b128 v[166:169], v136 offset:3072
	v_add_u32_e32 v136, s73, v153
	ds_read_b128 v[170:173], v136
	ds_read_b128 v[174:177], v136 offset:1024
	ds_read_b128 v[178:181], v136 offset:2048
	ds_read_b128 v[182:185], v136 offset:3072
	ds_read_b128 v[186:189], v157 offset:32768
	ds_read_b128 v[190:193], v157 offset:33792
	ds_read_b128 v[194:197], v157 offset:34816
	ds_read_b128 v[198:201], v157 offset:35840
	ds_read_b128 v[202:205], v157 offset:36864
	ds_read_b128 v[206:209], v157 offset:37888
	ds_read_b128 v[210:213], v157 offset:38912
	ds_read_b128 v[214:217], v157 offset:39936
	s_waitcnt vmcnt(8)
	s_waitcnt lgkmcnt(0)
	s_setprio 1
	s_barrier
	v_mfma_f32_16x16x32_bf16 v[124:127], v[146:149], v[186:189], v[124:127]
	v_mfma_f32_16x16x32_bf16 v[120:123], v[162:165], v[186:189], v[120:123]
	v_mfma_f32_16x16x32_bf16 v[108:111], v[146:149], v[194:197], v[108:111]
	v_mfma_f32_16x16x32_bf16 v[104:107], v[162:165], v[194:197], v[104:107]
	v_mfma_f32_16x16x32_bf16 v[92:95], v[146:149], v[202:205], v[92:95]
	v_mfma_f32_16x16x32_bf16 v[88:91], v[162:165], v[202:205], v[88:91]
	v_mfma_f32_16x16x32_bf16 v[76:79], v[146:149], v[210:213], v[76:79]
	v_mfma_f32_16x16x32_bf16 v[72:75], v[162:165], v[210:213], v[72:75]
	v_mfma_f32_16x16x32_bf16 v[124:127], v[158:161], v[190:193], v[124:127]
	v_mfma_f32_16x16x32_bf16 v[120:123], v[166:169], v[190:193], v[120:123]
	v_mfma_f32_16x16x32_bf16 v[108:111], v[158:161], v[198:201], v[108:111]
	v_mfma_f32_16x16x32_bf16 v[104:107], v[166:169], v[198:201], v[104:107]
	v_mfma_f32_16x16x32_bf16 v[92:95], v[158:161], v[206:209], v[92:95]
	v_mfma_f32_16x16x32_bf16 v[88:91], v[166:169], v[206:209], v[88:91]
	v_mfma_f32_16x16x32_bf16 v[76:79], v[158:161], v[214:217], v[76:79]
	v_mfma_f32_16x16x32_bf16 v[72:75], v[166:169], v[214:217], v[72:75]
	s_setprio 0
	s_setprio 1
	v_mfma_f32_16x16x32_bf16 v[116:119], v[170:173], v[186:189], v[116:119]
	v_mfma_f32_16x16x32_bf16 v[112:115], v[178:181], v[186:189], v[112:115]
	v_mfma_f32_16x16x32_bf16 v[100:103], v[170:173], v[194:197], v[100:103]
	v_mfma_f32_16x16x32_bf16 v[96:99], v[178:181], v[194:197], v[96:99]
	v_mfma_f32_16x16x32_bf16 v[84:87], v[170:173], v[202:205], v[84:87]
	v_mfma_f32_16x16x32_bf16 v[80:83], v[178:181], v[202:205], v[80:83]
	v_mfma_f32_16x16x32_bf16 v[68:71], v[170:173], v[210:213], v[68:71]
	v_mfma_f32_16x16x32_bf16 v[64:67], v[178:181], v[210:213], v[64:67]
	v_mfma_f32_16x16x32_bf16 v[116:119], v[174:177], v[190:193], v[116:119]
	v_mfma_f32_16x16x32_bf16 v[112:115], v[182:185], v[190:193], v[112:115]
	v_mfma_f32_16x16x32_bf16 v[100:103], v[174:177], v[198:201], v[100:103]
	v_mfma_f32_16x16x32_bf16 v[96:99], v[182:185], v[198:201], v[96:99]
	v_mfma_f32_16x16x32_bf16 v[84:87], v[174:177], v[206:209], v[84:87]
	v_mfma_f32_16x16x32_bf16 v[80:83], v[182:185], v[206:209], v[80:83]
	v_mfma_f32_16x16x32_bf16 v[68:71], v[174:177], v[214:217], v[68:71]
	v_mfma_f32_16x16x32_bf16 v[64:67], v[182:185], v[214:217], v[64:67]
	s_barrier
	s_setprio 0
	s_add_i32 s38, s72, s43
	v_lshl_add_u64 v[150:151], v[150:151], 0, s[12:13]
	s_mov_b32 m0, s38
	s_nop 0
	global_load_lds_dwordx4 v[150:151], off
	s_add_i32 m0, s38, 0x2000
	s_add_u32 s36, s36, 0x40080
	v_lshl_add_u64 v[150:151], v[218:219], 0, s[12:13]
	s_addc_u32 s37, s37, 0
	s_add_i32 s38, s73, s43
	global_load_lds_dwordx4 v[150:151], off
	v_lshl_add_u64 v[150:151], s[36:37], 0, v[130:131]
	s_mov_b32 m0, s38
	s_nop 0
	global_load_lds_dwordx4 v[150:151], off
	v_lshl_add_u64 v[150:151], s[36:37], 0, v[134:135]
	s_add_i32 m0, s38, 0x2000
	s_nop 0
	global_load_lds_dwordx4 v[150:151], off
	v_lshl_add_u64 v[150:151], v[220:221], 0, s[12:13]
	s_mov_b32 m0, s60
	s_nop 0
	global_load_lds_dwordx4 v[150:151], off
	v_lshl_add_u64 v[150:151], v[222:223], 0, s[12:13]
	s_mov_b32 m0, s61
	s_nop 0
	global_load_lds_dwordx4 v[150:151], off
	ds_read_b128 v[186:189], v157 offset:49152
	ds_read_b128 v[190:193], v157 offset:50176
	ds_read_b128 v[194:197], v157 offset:51200
	ds_read_b128 v[198:201], v157 offset:52224
	ds_read_b128 v[202:205], v157 offset:53248
	ds_read_b128 v[206:209], v157 offset:54272
	ds_read_b128 v[210:213], v157 offset:55296
	ds_read_b128 v[214:217], v157 offset:56320
	s_waitcnt vmcnt(8)
	s_waitcnt lgkmcnt(0)
	s_setprio 1
	s_barrier
	v_mfma_f32_16x16x32_bf16 v[60:63], v[146:149], v[186:189], v[60:63]
	v_mfma_f32_16x16x32_bf16 v[56:59], v[162:165], v[186:189], v[56:59]
	v_mfma_f32_16x16x32_bf16 v[44:47], v[146:149], v[194:197], v[44:47]
	v_mfma_f32_16x16x32_bf16 v[40:43], v[162:165], v[194:197], v[40:43]
	v_mfma_f32_16x16x32_bf16 v[28:31], v[146:149], v[202:205], v[28:31]
	v_mfma_f32_16x16x32_bf16 v[24:27], v[162:165], v[202:205], v[24:27]
	v_mfma_f32_16x16x32_bf16 v[12:15], v[146:149], v[210:213], v[12:15]
	v_mfma_f32_16x16x32_bf16 v[8:11], v[162:165], v[210:213], v[8:11]
	v_mfma_f32_16x16x32_bf16 v[60:63], v[158:161], v[190:193], v[60:63]
	v_mfma_f32_16x16x32_bf16 v[56:59], v[166:169], v[190:193], v[56:59]
	v_mfma_f32_16x16x32_bf16 v[44:47], v[158:161], v[198:201], v[44:47]
	v_mfma_f32_16x16x32_bf16 v[40:43], v[166:169], v[198:201], v[40:43]
	v_mfma_f32_16x16x32_bf16 v[28:31], v[158:161], v[206:209], v[28:31]
	v_mfma_f32_16x16x32_bf16 v[24:27], v[166:169], v[206:209], v[24:27]
	v_mfma_f32_16x16x32_bf16 v[12:15], v[158:161], v[214:217], v[12:15]
	v_mfma_f32_16x16x32_bf16 v[8:11], v[166:169], v[214:217], v[8:11]
	s_setprio 0
	s_setprio 1
	v_mfma_f32_16x16x32_bf16 v[52:55], v[170:173], v[186:189], v[52:55]
	v_mfma_f32_16x16x32_bf16 v[48:51], v[178:181], v[186:189], v[48:51]
	v_mfma_f32_16x16x32_bf16 v[36:39], v[170:173], v[194:197], v[36:39]
	v_mfma_f32_16x16x32_bf16 v[32:35], v[178:181], v[194:197], v[32:35]
	v_mfma_f32_16x16x32_bf16 v[20:23], v[170:173], v[202:205], v[20:23]
	v_mfma_f32_16x16x32_bf16 v[16:19], v[178:181], v[202:205], v[16:19]
	v_mfma_f32_16x16x32_bf16 v[4:7], v[170:173], v[210:213], v[4:7]
	v_mfma_f32_16x16x32_bf16 v[0:3], v[178:181], v[210:213], v[0:3]
	v_mfma_f32_16x16x32_bf16 v[52:55], v[174:177], v[190:193], v[52:55]
	v_mfma_f32_16x16x32_bf16 v[48:51], v[182:185], v[190:193], v[48:51]
	v_mfma_f32_16x16x32_bf16 v[36:39], v[174:177], v[198:201], v[36:39]
	v_mfma_f32_16x16x32_bf16 v[32:35], v[182:185], v[198:201], v[32:35]
	v_mfma_f32_16x16x32_bf16 v[20:23], v[174:177], v[206:209], v[20:23]
	v_mfma_f32_16x16x32_bf16 v[16:19], v[182:185], v[206:209], v[16:19]
	v_mfma_f32_16x16x32_bf16 v[4:7], v[174:177], v[214:217], v[4:7]
	v_mfma_f32_16x16x32_bf16 v[0:3], v[182:185], v[214:217], v[0:3]
	s_barrier
	s_setprio 0
	s_add_i32 s71, s71, 2
	s_add_u32 s34, s34, 0x100
	s_addc_u32 s35, s35, 0
	s_add_u32 s69, s69, 0x100
	s_addc_u32 s70, s70, 0
	s_cmp_gt_u32 s71, 13
	s_cbranch_scc0 .LBB0_217
	s_and_b64 vcc, exec, s[14:15]
	s_cbranch_vccz .LBB0_220
	s_barrier

.LBB0_471:
	s_add_u32 s34, s30, 0xfffc0080
	s_addc_u32 s35, s31, -1
	s_cmp_eq_u32 s69, 12
	s_cselect_b32 s37, s21, s35
	s_cselect_b32 s36, s27, s34
	s_cselect_b32 s35, s19, s68
	s_cselect_b32 s34, s64, s65
	v_lshl_add_u64 v[214:215], s[30:31], 0, v[184:185]
	s_add_i32 m0, s29, 0xc000
	s_nop 0
	global_load_lds_dwordx4 v[214:215], off
	v_lshl_add_u64 v[214:215], s[30:31], 0, v[186:187]
	s_add_i32 m0, s29, 0xe000
	s_nop 0
	global_load_lds_dwordx4 v[214:215], off
	ds_read_b128 v[128:131], v207
	ds_read_b128 v[132:135], v207 offset:1024
	ds_read_b128 v[136:139], v207 offset:2048
	ds_read_b128 v[140:143], v207 offset:3072
	ds_read_b128 v[144:147], v208
	ds_read_b128 v[148:151], v208 offset:1024
	ds_read_b128 v[152:155], v208 offset:2048
	ds_read_b128 v[156:159], v208 offset:3072
	ds_read_b128 v[160:163], v209
	ds_read_b128 v[164:167], v209 offset:1024
	ds_read_b128 v[168:171], v209 offset:2048
	ds_read_b128 v[172:175], v209 offset:3072
	ds_read_b128 v[192:195], v209 offset:4096
	ds_read_b128 v[196:199], v209 offset:5120
	ds_read_b128 v[200:203], v209 offset:6144
	ds_read_b128 v[210:213], v209 offset:7168
	s_waitcnt vmcnt(8)
	s_waitcnt lgkmcnt(0)
	s_setprio 1
	s_barrier
	v_mfma_f32_16x16x32_bf16 v[124:127], v[128:131], v[160:163], v[124:127]
	v_mfma_f32_16x16x32_bf16 v[120:123], v[136:139], v[160:163], v[120:123]
	v_mfma_f32_16x16x32_bf16 v[108:111], v[128:131], v[168:171], v[108:111]
	v_mfma_f32_16x16x32_bf16 v[104:107], v[136:139], v[168:171], v[104:107]
	v_mfma_f32_16x16x32_bf16 v[92:95], v[128:131], v[192:195], v[92:95]
	v_mfma_f32_16x16x32_bf16 v[88:91], v[136:139], v[192:195], v[88:91]
	v_mfma_f32_16x16x32_bf16 v[76:79], v[128:131], v[200:203], v[76:79]
	v_mfma_f32_16x16x32_bf16 v[72:75], v[136:139], v[200:203], v[72:75]
	v_mfma_f32_16x16x32_bf16 v[124:127], v[132:135], v[164:167], v[124:127]
	v_mfma_f32_16x16x32_bf16 v[120:123], v[140:143], v[164:167], v[120:123]
	v_mfma_f32_16x16x32_bf16 v[108:111], v[132:135], v[172:175], v[108:111]
	v_mfma_f32_16x16x32_bf16 v[104:107], v[140:143], v[172:175], v[104:107]
	v_mfma_f32_16x16x32_bf16 v[92:95], v[132:135], v[196:199], v[92:95]
	v_mfma_f32_16x16x32_bf16 v[88:91], v[140:143], v[196:199], v[88:91]
	v_mfma_f32_16x16x32_bf16 v[76:79], v[132:135], v[210:213], v[76:79]
	v_mfma_f32_16x16x32_bf16 v[72:75], v[140:143], v[210:213], v[72:75]
	s_setprio 0
	s_setprio 1
	v_mfma_f32_16x16x32_bf16 v[116:119], v[144:147], v[160:163], v[116:119]
	v_mfma_f32_16x16x32_bf16 v[112:115], v[152:155], v[160:163], v[112:115]
	v_mfma_f32_16x16x32_bf16 v[100:103], v[144:147], v[168:171], v[100:103]
	v_mfma_f32_16x16x32_bf16 v[96:99], v[152:155], v[168:171], v[96:99]
	v_mfma_f32_16x16x32_bf16 v[84:87], v[144:147], v[192:195], v[84:87]
	v_mfma_f32_16x16x32_bf16 v[80:83], v[152:155], v[192:195], v[80:83]
	v_mfma_f32_16x16x32_bf16 v[68:71], v[144:147], v[200:203], v[68:71]
	v_mfma_f32_16x16x32_bf16 v[64:67], v[152:155], v[200:203], v[64:67]
	v_mfma_f32_16x16x32_bf16 v[116:119], v[148:151], v[164:167], v[116:119]
	v_mfma_f32_16x16x32_bf16 v[112:115], v[156:159], v[164:167], v[112:115]
	v_mfma_f32_16x16x32_bf16 v[100:103], v[148:151], v[172:175], v[100:103]
	v_mfma_f32_16x16x32_bf16 v[96:99], v[156:159], v[172:175], v[96:99]
	v_mfma_f32_16x16x32_bf16 v[84:87], v[148:151], v[196:199], v[84:87]
	v_mfma_f32_16x16x32_bf16 v[80:83], v[156:159], v[196:199], v[80:83]
	v_mfma_f32_16x16x32_bf16 v[68:71], v[148:151], v[210:213], v[68:71]
	v_mfma_f32_16x16x32_bf16 v[64:67], v[156:159], v[210:213], v[64:67]
	s_barrier
	s_setprio 0
	s_add_i32 s70, s62, s40
	v_lshl_add_u64 v[214:215], s[34:35], 0, v[178:179]
	s_mov_b32 m0, s70
	s_nop 0
	global_load_lds_dwordx4 v[214:215], off
	s_add_i32 m0, s70, 0x2000
	s_add_u32 s70, s34, 0x40000
	v_lshl_add_u64 v[216:217], s[34:35], 0, v[182:183]
	s_addc_u32 s71, s35, 0
	s_add_i32 s72, s63, s40
	global_load_lds_dwordx4 v[216:217], off
	v_lshl_add_u64 v[218:219], s[70:71], 0, v[178:179]
	s_mov_b32 m0, s72
	v_lshl_add_u64 v[220:221], s[36:37], 0, v[180:181]
	global_load_lds_dwordx4 v[218:219], off
	v_lshl_add_u64 v[218:219], s[70:71], 0, v[182:183]
	s_add_i32 m0, s72, 0x2000
	s_nop 0
	global_load_lds_dwordx4 v[218:219], off
	v_lshl_add_u64 v[218:219], s[36:37], 0, v[176:177]
	s_mov_b32 m0, s29
	s_nop 0
	global_load_lds_dwordx4 v[218:219], off
	s_mov_b32 m0, s41
	s_nop 0
	global_load_lds_dwordx4 v[220:221], off
	ds_read_b128 v[160:163], v209 offset:16384
	ds_read_b128 v[164:167], v209 offset:17408
	ds_read_b128 v[168:171], v209 offset:18432
	ds_read_b128 v[172:175], v209 offset:19456
	ds_read_b128 v[192:195], v209 offset:20480
	ds_read_b128 v[196:199], v209 offset:21504
	ds_read_b128 v[200:203], v209 offset:22528
	ds_read_b128 v[210:213], v209 offset:23552
	s_waitcnt vmcnt(8)
	s_waitcnt lgkmcnt(0)
	s_setprio 1
	s_barrier
	v_mfma_f32_16x16x32_bf16 v[60:63], v[128:131], v[160:163], v[60:63]
	v_mfma_f32_16x16x32_bf16 v[56:59], v[136:139], v[160:163], v[56:59]
	v_mfma_f32_16x16x32_bf16 v[44:47], v[128:131], v[168:171], v[44:47]
	v_mfma_f32_16x16x32_bf16 v[40:43], v[136:139], v[168:171], v[40:43]
	v_mfma_f32_16x16x32_bf16 v[28:31], v[128:131], v[192:195], v[28:31]
	v_mfma_f32_16x16x32_bf16 v[24:27], v[136:139], v[192:195], v[24:27]
	v_mfma_f32_16x16x32_bf16 v[12:15], v[128:131], v[200:203], v[12:15]
	v_mfma_f32_16x16x32_bf16 v[8:11], v[136:139], v[200:203], v[8:11]
	v_mfma_f32_16x16x32_bf16 v[60:63], v[132:135], v[164:167], v[60:63]
	v_mfma_f32_16x16x32_bf16 v[56:59], v[140:143], v[164:167], v[56:59]
	v_mfma_f32_16x16x32_bf16 v[44:47], v[132:135], v[172:175], v[44:47]
	v_mfma_f32_16x16x32_bf16 v[40:43], v[140:143], v[172:175], v[40:43]
	v_mfma_f32_16x16x32_bf16 v[28:31], v[132:135], v[196:199], v[28:31]
	v_mfma_f32_16x16x32_bf16 v[24:27], v[140:143], v[196:199], v[24:27]
	v_mfma_f32_16x16x32_bf16 v[12:15], v[132:135], v[210:213], v[12:15]
	v_mfma_f32_16x16x32_bf16 v[8:11], v[140:143], v[210:213], v[8:11]
	s_setprio 0
	s_setprio 1
	v_mfma_f32_16x16x32_bf16 v[52:55], v[144:147], v[160:163], v[52:55]
	v_mfma_f32_16x16x32_bf16 v[48:51], v[152:155], v[160:163], v[48:51]
	v_mfma_f32_16x16x32_bf16 v[36:39], v[144:147], v[168:171], v[36:39]
	v_mfma_f32_16x16x32_bf16 v[32:35], v[152:155], v[168:171], v[32:35]
	v_mfma_f32_16x16x32_bf16 v[20:23], v[144:147], v[192:195], v[20:23]
	v_mfma_f32_16x16x32_bf16 v[16:19], v[152:155], v[192:195], v[16:19]
	v_mfma_f32_16x16x32_bf16 v[4:7], v[144:147], v[200:203], v[4:7]
	v_mfma_f32_16x16x32_bf16 v[0:3], v[152:155], v[200:203], v[0:3]
	v_mfma_f32_16x16x32_bf16 v[52:55], v[148:151], v[164:167], v[52:55]
	v_mfma_f32_16x16x32_bf16 v[48:51], v[156:159], v[164:167], v[48:51]
	v_mfma_f32_16x16x32_bf16 v[36:39], v[148:151], v[172:175], v[36:39]
	v_mfma_f32_16x16x32_bf16 v[32:35], v[156:159], v[172:175], v[32:35]
	v_mfma_f32_16x16x32_bf16 v[20:23], v[148:151], v[196:199], v[20:23]
	v_mfma_f32_16x16x32_bf16 v[16:19], v[156:159], v[196:199], v[16:19]
	v_mfma_f32_16x16x32_bf16 v[4:7], v[148:151], v[210:213], v[4:7]
	v_mfma_f32_16x16x32_bf16 v[0:3], v[156:159], v[210:213], v[0:3]
	s_barrier
	s_setprio 0
	s_add_i32 s70, 0, 0x18000
	s_add_i32 s71, 0, 0x1c000
	s_add_u32 s36, s36, 0x40000
	s_addc_u32 s37, s37, 0
	s_mov_b32 m0, s42
	v_lshl_add_u64 v[222:223], s[36:37], 0, v[176:177]
	global_load_lds_dwordx4 v[222:223], off
	v_lshl_add_u64 v[222:223], s[36:37], 0, v[180:181]
	s_mov_b32 m0, s43
	s_nop 0
	global_load_lds_dwordx4 v[222:223], off
	v_add_u32_e32 v140, s70, v206
	v_add_u32_e32 v156, s71, v206
	ds_read_b128 v[128:131], v140
	ds_read_b128 v[132:135], v140 offset:1024
	ds_read_b128 v[136:139], v140 offset:2048
	ds_read_b128 v[140:143], v140 offset:3072
	ds_read_b128 v[144:147], v156
	ds_read_b128 v[148:151], v156 offset:1024
	ds_read_b128 v[152:155], v156 offset:2048
	ds_read_b128 v[156:159], v156 offset:3072
	ds_read_b128 v[160:163], v209 offset:32768
	ds_read_b128 v[164:167], v209 offset:33792
	ds_read_b128 v[168:171], v209 offset:34816
	ds_read_b128 v[172:175], v209 offset:35840
	ds_read_b128 v[192:195], v209 offset:36864
	ds_read_b128 v[196:199], v209 offset:37888
	ds_read_b128 v[200:203], v209 offset:38912
	ds_read_b128 v[210:213], v209 offset:39936
	s_waitcnt vmcnt(8)
	s_waitcnt lgkmcnt(0)
	s_setprio 1
	s_barrier
	v_mfma_f32_16x16x32_bf16 v[124:127], v[128:131], v[160:163], v[124:127]
	v_mfma_f32_16x16x32_bf16 v[120:123], v[136:139], v[160:163], v[120:123]
	v_mfma_f32_16x16x32_bf16 v[108:111], v[128:131], v[168:171], v[108:111]
	v_mfma_f32_16x16x32_bf16 v[104:107], v[136:139], v[168:171], v[104:107]
	v_mfma_f32_16x16x32_bf16 v[92:95], v[128:131], v[192:195], v[92:95]
	v_mfma_f32_16x16x32_bf16 v[88:91], v[136:139], v[192:195], v[88:91]
	v_mfma_f32_16x16x32_bf16 v[76:79], v[128:131], v[200:203], v[76:79]
	v_mfma_f32_16x16x32_bf16 v[72:75], v[136:139], v[200:203], v[72:75]
	v_mfma_f32_16x16x32_bf16 v[124:127], v[132:135], v[164:167], v[124:127]
	v_mfma_f32_16x16x32_bf16 v[120:123], v[140:143], v[164:167], v[120:123]
	v_mfma_f32_16x16x32_bf16 v[108:111], v[132:135], v[172:175], v[108:111]
	v_mfma_f32_16x16x32_bf16 v[104:107], v[140:143], v[172:175], v[104:107]
	v_mfma_f32_16x16x32_bf16 v[92:95], v[132:135], v[196:199], v[92:95]
	v_mfma_f32_16x16x32_bf16 v[88:91], v[140:143], v[196:199], v[88:91]
	v_mfma_f32_16x16x32_bf16 v[76:79], v[132:135], v[210:213], v[76:79]
	v_mfma_f32_16x16x32_bf16 v[72:75], v[140:143], v[210:213], v[72:75]
	s_setprio 0
	s_setprio 1
	v_mfma_f32_16x16x32_bf16 v[116:119], v[144:147], v[160:163], v[116:119]
	v_mfma_f32_16x16x32_bf16 v[112:115], v[152:155], v[160:163], v[112:115]
	v_mfma_f32_16x16x32_bf16 v[100:103], v[144:147], v[168:171], v[100:103]
	v_mfma_f32_16x16x32_bf16 v[96:99], v[152:155], v[168:171], v[96:99]
	v_mfma_f32_16x16x32_bf16 v[84:87], v[144:147], v[192:195], v[84:87]
	v_mfma_f32_16x16x32_bf16 v[80:83], v[152:155], v[192:195], v[80:83]
	v_mfma_f32_16x16x32_bf16 v[68:71], v[144:147], v[200:203], v[68:71]
	v_mfma_f32_16x16x32_bf16 v[64:67], v[152:155], v[200:203], v[64:67]
	v_mfma_f32_16x16x32_bf16 v[116:119], v[148:151], v[164:167], v[116:119]
	v_mfma_f32_16x16x32_bf16 v[112:115], v[156:159], v[164:167], v[112:115]
	v_mfma_f32_16x16x32_bf16 v[100:103], v[148:151], v[172:175], v[100:103]
	v_mfma_f32_16x16x32_bf16 v[96:99], v[156:159], v[172:175], v[96:99]
	v_mfma_f32_16x16x32_bf16 v[84:87], v[148:151], v[196:199], v[84:87]
	v_mfma_f32_16x16x32_bf16 v[80:83], v[156:159], v[196:199], v[80:83]
	v_mfma_f32_16x16x32_bf16 v[68:71], v[148:151], v[210:213], v[68:71]
	v_mfma_f32_16x16x32_bf16 v[64:67], v[156:159], v[210:213], v[64:67]
	s_barrier
	s_setprio 0
	s_add_i32 s36, s70, s40
	v_lshl_add_u64 v[214:215], v[214:215], 0, s[14:15]
	s_mov_b32 m0, s36
	s_nop 0
	global_load_lds_dwordx4 v[214:215], off
	s_add_i32 m0, s36, 0x2000
	s_add_u32 s34, s34, 0x40080
	v_lshl_add_u64 v[214:215], v[216:217], 0, s[14:15]
	s_addc_u32 s35, s35, 0
	s_add_i32 s36, s71, s40
	global_load_lds_dwordx4 v[214:215], off
	v_lshl_add_u64 v[214:215], s[34:35], 0, v[178:179]
	s_mov_b32 m0, s36
	s_nop 0
	global_load_lds_dwordx4 v[214:215], off
	v_lshl_add_u64 v[214:215], s[34:35], 0, v[182:183]
	s_add_i32 m0, s36, 0x2000
	s_nop 0
	global_load_lds_dwordx4 v[214:215], off
	v_lshl_add_u64 v[214:215], v[218:219], 0, s[14:15]
	s_mov_b32 m0, s49
	s_nop 0
	global_load_lds_dwordx4 v[214:215], off
	v_lshl_add_u64 v[214:215], v[220:221], 0, s[14:15]
	s_mov_b32 m0, s50
	s_nop 0
	global_load_lds_dwordx4 v[214:215], off
	ds_read_b128 v[160:163], v209 offset:49152
	ds_read_b128 v[164:167], v209 offset:50176
	ds_read_b128 v[168:171], v209 offset:51200
	ds_read_b128 v[172:175], v209 offset:52224
	ds_read_b128 v[192:195], v209 offset:53248
	ds_read_b128 v[196:199], v209 offset:54272
	ds_read_b128 v[200:203], v209 offset:55296
	ds_read_b128 v[210:213], v209 offset:56320
	s_waitcnt vmcnt(8)
	s_waitcnt lgkmcnt(0)
	s_setprio 1
	s_barrier
	v_mfma_f32_16x16x32_bf16 v[60:63], v[128:131], v[160:163], v[60:63]
	v_mfma_f32_16x16x32_bf16 v[56:59], v[136:139], v[160:163], v[56:59]
	v_mfma_f32_16x16x32_bf16 v[44:47], v[128:131], v[168:171], v[44:47]
	v_mfma_f32_16x16x32_bf16 v[40:43], v[136:139], v[168:171], v[40:43]
	v_mfma_f32_16x16x32_bf16 v[28:31], v[128:131], v[192:195], v[28:31]
	v_mfma_f32_16x16x32_bf16 v[24:27], v[136:139], v[192:195], v[24:27]
	v_mfma_f32_16x16x32_bf16 v[12:15], v[128:131], v[200:203], v[12:15]
	v_mfma_f32_16x16x32_bf16 v[8:11], v[136:139], v[200:203], v[8:11]
	v_mfma_f32_16x16x32_bf16 v[60:63], v[132:135], v[164:167], v[60:63]
	v_mfma_f32_16x16x32_bf16 v[56:59], v[140:143], v[164:167], v[56:59]
	v_mfma_f32_16x16x32_bf16 v[44:47], v[132:135], v[172:175], v[44:47]
	v_mfma_f32_16x16x32_bf16 v[40:43], v[140:143], v[172:175], v[40:43]
	v_mfma_f32_16x16x32_bf16 v[28:31], v[132:135], v[196:199], v[28:31]
	v_mfma_f32_16x16x32_bf16 v[24:27], v[140:143], v[196:199], v[24:27]
	v_mfma_f32_16x16x32_bf16 v[12:15], v[132:135], v[210:213], v[12:15]
	v_mfma_f32_16x16x32_bf16 v[8:11], v[140:143], v[210:213], v[8:11]
	s_setprio 0
	s_setprio 1
	v_mfma_f32_16x16x32_bf16 v[52:55], v[144:147], v[160:163], v[52:55]
	v_mfma_f32_16x16x32_bf16 v[48:51], v[152:155], v[160:163], v[48:51]
	v_mfma_f32_16x16x32_bf16 v[36:39], v[144:147], v[168:171], v[36:39]
	v_mfma_f32_16x16x32_bf16 v[32:35], v[152:155], v[168:171], v[32:35]
	v_mfma_f32_16x16x32_bf16 v[20:23], v[144:147], v[192:195], v[20:23]
	v_mfma_f32_16x16x32_bf16 v[16:19], v[152:155], v[192:195], v[16:19]
	v_mfma_f32_16x16x32_bf16 v[4:7], v[144:147], v[200:203], v[4:7]
	v_mfma_f32_16x16x32_bf16 v[0:3], v[152:155], v[200:203], v[0:3]
	v_mfma_f32_16x16x32_bf16 v[52:55], v[148:151], v[164:167], v[52:55]
	v_mfma_f32_16x16x32_bf16 v[48:51], v[156:159], v[164:167], v[48:51]
	v_mfma_f32_16x16x32_bf16 v[36:39], v[148:151], v[172:175], v[36:39]
	v_mfma_f32_16x16x32_bf16 v[32:35], v[156:159], v[172:175], v[32:35]
	v_mfma_f32_16x16x32_bf16 v[20:23], v[148:151], v[196:199], v[20:23]
	v_mfma_f32_16x16x32_bf16 v[16:19], v[156:159], v[196:199], v[16:19]
	v_mfma_f32_16x16x32_bf16 v[4:7], v[148:151], v[210:213], v[4:7]
	v_mfma_f32_16x16x32_bf16 v[0:3], v[156:159], v[210:213], v[0:3]
	s_barrier
	s_setprio 0
	s_add_i32 s69, s69, 2
	s_add_u32 s30, s30, 0x100
	s_addc_u32 s31, s31, 0
	s_add_u32 s65, s65, 0x100
	s_addc_u32 s68, s68, 0
	s_cmp_gt_u32 s69, 13
	s_cbranch_scc0 .LBB0_471
	s_and_b64 vcc, exec, s[16:17]
	s_cbranch_vccz .LBB0_474
	s_barrier

.LBB0_555:
	s_add_u32 s30, s28, 0xfffc0080
	s_addc_u32 s31, s29, -1
	s_cmp_eq_u32 s63, 12
	s_cselect_b32 s35, s19, s31
	s_cselect_b32 s34, s51, s30
	s_cselect_b32 s31, s17, s62
	s_cselect_b32 s30, s60, s61
	v_lshl_add_u64 v[144:145], s[28:29], 0, v[136:137]
	s_add_i32 m0, s25, 0xc000
	s_nop 0
	global_load_lds_dwordx4 v[144:145], off
	v_lshl_add_u64 v[144:145], s[28:29], 0, v[138:139]
	s_add_i32 m0, s25, 0xe000
	s_nop 0
	global_load_lds_dwordx4 v[144:145], off
	ds_read_b128 v[154:157], v149
	ds_read_b128 v[158:161], v149 offset:1024
	ds_read_b128 v[162:165], v149 offset:2048
	ds_read_b128 v[166:169], v149 offset:3072
	ds_read_b128 v[170:173], v150
	ds_read_b128 v[174:177], v150 offset:1024
	ds_read_b128 v[178:181], v150 offset:2048
	ds_read_b128 v[182:185], v150 offset:3072
	ds_read_b128 v[186:189], v151
	ds_read_b128 v[190:193], v151 offset:1024
	ds_read_b128 v[194:197], v151 offset:2048
	ds_read_b128 v[198:201], v151 offset:3072
	ds_read_b128 v[202:205], v151 offset:4096
	ds_read_b128 v[206:209], v151 offset:5120
	ds_read_b128 v[210:213], v151 offset:6144
	ds_read_b128 v[214:217], v151 offset:7168
	s_waitcnt vmcnt(8)
	s_waitcnt lgkmcnt(0)
	s_setprio 1
	s_barrier
	v_mfma_f32_16x16x32_bf16 v[116:119], v[154:157], v[186:189], v[116:119]
	v_mfma_f32_16x16x32_bf16 v[112:115], v[162:165], v[186:189], v[112:115]
	v_mfma_f32_16x16x32_bf16 v[108:111], v[154:157], v[194:197], v[108:111]
	v_mfma_f32_16x16x32_bf16 v[100:103], v[162:165], v[194:197], v[100:103]
	v_mfma_f32_16x16x32_bf16 v[92:95], v[154:157], v[202:205], v[92:95]
	v_mfma_f32_16x16x32_bf16 v[84:87], v[162:165], v[202:205], v[84:87]
	v_mfma_f32_16x16x32_bf16 v[76:79], v[154:157], v[210:213], v[76:79]
	v_mfma_f32_16x16x32_bf16 v[68:71], v[162:165], v[210:213], v[68:71]
	v_mfma_f32_16x16x32_bf16 v[116:119], v[158:161], v[190:193], v[116:119]
	v_mfma_f32_16x16x32_bf16 v[112:115], v[166:169], v[190:193], v[112:115]
	v_mfma_f32_16x16x32_bf16 v[108:111], v[158:161], v[198:201], v[108:111]
	v_mfma_f32_16x16x32_bf16 v[100:103], v[166:169], v[198:201], v[100:103]
	v_mfma_f32_16x16x32_bf16 v[92:95], v[158:161], v[206:209], v[92:95]
	v_mfma_f32_16x16x32_bf16 v[84:87], v[166:169], v[206:209], v[84:87]
	v_mfma_f32_16x16x32_bf16 v[76:79], v[158:161], v[214:217], v[76:79]
	v_mfma_f32_16x16x32_bf16 v[68:71], v[166:169], v[214:217], v[68:71]
	s_setprio 0
	s_setprio 1
	v_mfma_f32_16x16x32_bf16 v[124:127], v[170:173], v[186:189], v[124:127]
	v_mfma_f32_16x16x32_bf16 v[120:123], v[178:181], v[186:189], v[120:123]
	v_mfma_f32_16x16x32_bf16 v[104:107], v[170:173], v[194:197], v[104:107]
	v_mfma_f32_16x16x32_bf16 v[96:99], v[178:181], v[194:197], v[96:99]
	v_mfma_f32_16x16x32_bf16 v[88:91], v[170:173], v[202:205], v[88:91]
	v_mfma_f32_16x16x32_bf16 v[80:83], v[178:181], v[202:205], v[80:83]
	v_mfma_f32_16x16x32_bf16 v[72:75], v[170:173], v[210:213], v[72:75]
	v_mfma_f32_16x16x32_bf16 v[64:67], v[178:181], v[210:213], v[64:67]
	v_mfma_f32_16x16x32_bf16 v[124:127], v[174:177], v[190:193], v[124:127]
	v_mfma_f32_16x16x32_bf16 v[120:123], v[182:185], v[190:193], v[120:123]
	v_mfma_f32_16x16x32_bf16 v[104:107], v[174:177], v[198:201], v[104:107]
	v_mfma_f32_16x16x32_bf16 v[96:99], v[182:185], v[198:201], v[96:99]
	v_mfma_f32_16x16x32_bf16 v[88:91], v[174:177], v[206:209], v[88:91]
	v_mfma_f32_16x16x32_bf16 v[80:83], v[182:185], v[206:209], v[80:83]
	v_mfma_f32_16x16x32_bf16 v[72:75], v[174:177], v[214:217], v[72:75]
	v_mfma_f32_16x16x32_bf16 v[64:67], v[182:185], v[214:217], v[64:67]
	s_barrier
	s_setprio 0
	s_add_i32 s64, s48, s36
	v_lshl_add_u64 v[144:145], s[30:31], 0, v[132:133]
	s_mov_b32 m0, s64
	s_nop 0
	global_load_lds_dwordx4 v[144:145], off
	s_add_i32 m0, s64, 0x2000
	s_add_u32 s64, s30, 0x40000
	v_lshl_add_u64 v[218:219], s[30:31], 0, v[128:129]
	s_addc_u32 s65, s31, 0
	s_add_i32 s68, s49, s36
	global_load_lds_dwordx4 v[218:219], off
	v_lshl_add_u64 v[220:221], s[64:65], 0, v[132:133]
	s_mov_b32 m0, s68
	v_lshl_add_u64 v[222:223], s[34:35], 0, v[130:131]
	global_load_lds_dwordx4 v[220:221], off
	v_lshl_add_u64 v[220:221], s[64:65], 0, v[128:129]
	s_add_i32 m0, s68, 0x2000
	s_nop 0
	global_load_lds_dwordx4 v[220:221], off
	v_lshl_add_u64 v[220:221], s[34:35], 0, v[134:135]
	s_mov_b32 m0, s25
	s_nop 0
	global_load_lds_dwordx4 v[220:221], off
	s_mov_b32 m0, s27
	s_nop 0
	global_load_lds_dwordx4 v[222:223], off
	ds_read_b128 v[186:189], v151 offset:16384
	ds_read_b128 v[190:193], v151 offset:17408
	ds_read_b128 v[194:197], v151 offset:18432
	ds_read_b128 v[198:201], v151 offset:19456
	ds_read_b128 v[202:205], v151 offset:20480
	ds_read_b128 v[206:209], v151 offset:21504
	ds_read_b128 v[210:213], v151 offset:22528
	ds_read_b128 v[214:217], v151 offset:23552
	s_waitcnt vmcnt(8)
	s_waitcnt lgkmcnt(0)
	s_setprio 1
	s_barrier
	v_mfma_f32_16x16x32_bf16 v[60:63], v[154:157], v[186:189], v[60:63]
	v_mfma_f32_16x16x32_bf16 v[52:55], v[162:165], v[186:189], v[52:55]
	v_mfma_f32_16x16x32_bf16 v[44:47], v[154:157], v[194:197], v[44:47]
	v_mfma_f32_16x16x32_bf16 v[36:39], v[162:165], v[194:197], v[36:39]
	v_mfma_f32_16x16x32_bf16 v[28:31], v[154:157], v[202:205], v[28:31]
	v_mfma_f32_16x16x32_bf16 v[20:23], v[162:165], v[202:205], v[20:23]
	v_mfma_f32_16x16x32_bf16 v[12:15], v[154:157], v[210:213], v[12:15]
	v_mfma_f32_16x16x32_bf16 v[4:7], v[162:165], v[210:213], v[4:7]
	v_mfma_f32_16x16x32_bf16 v[60:63], v[158:161], v[190:193], v[60:63]
	v_mfma_f32_16x16x32_bf16 v[52:55], v[166:169], v[190:193], v[52:55]
	v_mfma_f32_16x16x32_bf16 v[44:47], v[158:161], v[198:201], v[44:47]
	v_mfma_f32_16x16x32_bf16 v[36:39], v[166:169], v[198:201], v[36:39]
	v_mfma_f32_16x16x32_bf16 v[28:31], v[158:161], v[206:209], v[28:31]
	v_mfma_f32_16x16x32_bf16 v[20:23], v[166:169], v[206:209], v[20:23]
	v_mfma_f32_16x16x32_bf16 v[12:15], v[158:161], v[214:217], v[12:15]
	v_mfma_f32_16x16x32_bf16 v[4:7], v[166:169], v[214:217], v[4:7]
	s_setprio 0
	s_setprio 1
	v_mfma_f32_16x16x32_bf16 v[56:59], v[170:173], v[186:189], v[56:59]
	v_mfma_f32_16x16x32_bf16 v[48:51], v[178:181], v[186:189], v[48:51]
	v_mfma_f32_16x16x32_bf16 v[40:43], v[170:173], v[194:197], v[40:43]
	v_mfma_f32_16x16x32_bf16 v[32:35], v[178:181], v[194:197], v[32:35]
	v_mfma_f32_16x16x32_bf16 v[24:27], v[170:173], v[202:205], v[24:27]
	v_mfma_f32_16x16x32_bf16 v[16:19], v[178:181], v[202:205], v[16:19]
	v_mfma_f32_16x16x32_bf16 v[8:11], v[170:173], v[210:213], v[8:11]
	v_mfma_f32_16x16x32_bf16 v[0:3], v[178:181], v[210:213], v[0:3]
	v_mfma_f32_16x16x32_bf16 v[56:59], v[174:177], v[190:193], v[56:59]
	v_mfma_f32_16x16x32_bf16 v[48:51], v[182:185], v[190:193], v[48:51]
	v_mfma_f32_16x16x32_bf16 v[40:43], v[174:177], v[198:201], v[40:43]
	v_mfma_f32_16x16x32_bf16 v[32:35], v[182:185], v[198:201], v[32:35]
	v_mfma_f32_16x16x32_bf16 v[24:27], v[174:177], v[206:209], v[24:27]
	v_mfma_f32_16x16x32_bf16 v[16:19], v[182:185], v[206:209], v[16:19]
	v_mfma_f32_16x16x32_bf16 v[8:11], v[174:177], v[214:217], v[8:11]
	v_mfma_f32_16x16x32_bf16 v[0:3], v[182:185], v[214:217], v[0:3]
	s_barrier
	s_setprio 0
	s_add_i32 s64, 0, 0x18000
	s_add_i32 s65, 0, 0x1c000
	s_add_u32 s34, s34, 0x40000
	s_addc_u32 s35, s35, 0
	s_mov_b32 m0, s39
	v_lshl_add_u64 v[224:225], s[34:35], 0, v[134:135]
	global_load_lds_dwordx4 v[224:225], off
	v_lshl_add_u64 v[224:225], s[34:35], 0, v[130:131]
	s_mov_b32 m0, s40
	s_nop 0
	global_load_lds_dwordx4 v[224:225], off
	v_add_u32_e32 v153, s64, v147
	ds_read_b128 v[154:157], v153
	ds_read_b128 v[158:161], v153 offset:1024
	ds_read_b128 v[162:165], v153 offset:2048
	ds_read_b128 v[166:169], v153 offset:3072
	v_add_u32_e32 v153, s65, v147
	ds_read_b128 v[170:173], v153
	ds_read_b128 v[174:177], v153 offset:1024
	ds_read_b128 v[178:181], v153 offset:2048
	ds_read_b128 v[182:185], v153 offset:3072
	ds_read_b128 v[186:189], v151 offset:32768
	ds_read_b128 v[190:193], v151 offset:33792
	ds_read_b128 v[194:197], v151 offset:34816
	ds_read_b128 v[198:201], v151 offset:35840
	ds_read_b128 v[202:205], v151 offset:36864
	ds_read_b128 v[206:209], v151 offset:37888
	ds_read_b128 v[210:213], v151 offset:38912
	ds_read_b128 v[214:217], v151 offset:39936
	s_waitcnt vmcnt(8)
	s_waitcnt lgkmcnt(0)
	s_setprio 1
	s_barrier
	v_mfma_f32_16x16x32_bf16 v[116:119], v[154:157], v[186:189], v[116:119]
	v_mfma_f32_16x16x32_bf16 v[112:115], v[162:165], v[186:189], v[112:115]
	v_mfma_f32_16x16x32_bf16 v[108:111], v[154:157], v[194:197], v[108:111]
	v_mfma_f32_16x16x32_bf16 v[100:103], v[162:165], v[194:197], v[100:103]
	v_mfma_f32_16x16x32_bf16 v[92:95], v[154:157], v[202:205], v[92:95]
	v_mfma_f32_16x16x32_bf16 v[84:87], v[162:165], v[202:205], v[84:87]
	v_mfma_f32_16x16x32_bf16 v[76:79], v[154:157], v[210:213], v[76:79]
	v_mfma_f32_16x16x32_bf16 v[68:71], v[162:165], v[210:213], v[68:71]
	v_mfma_f32_16x16x32_bf16 v[116:119], v[158:161], v[190:193], v[116:119]
	v_mfma_f32_16x16x32_bf16 v[112:115], v[166:169], v[190:193], v[112:115]
	v_mfma_f32_16x16x32_bf16 v[108:111], v[158:161], v[198:201], v[108:111]
	v_mfma_f32_16x16x32_bf16 v[100:103], v[166:169], v[198:201], v[100:103]
	v_mfma_f32_16x16x32_bf16 v[92:95], v[158:161], v[206:209], v[92:95]
	v_mfma_f32_16x16x32_bf16 v[84:87], v[166:169], v[206:209], v[84:87]
	v_mfma_f32_16x16x32_bf16 v[76:79], v[158:161], v[214:217], v[76:79]
	v_mfma_f32_16x16x32_bf16 v[68:71], v[166:169], v[214:217], v[68:71]
	s_setprio 0
	s_setprio 1
	v_mfma_f32_16x16x32_bf16 v[124:127], v[170:173], v[186:189], v[124:127]
	v_mfma_f32_16x16x32_bf16 v[120:123], v[178:181], v[186:189], v[120:123]
	v_mfma_f32_16x16x32_bf16 v[104:107], v[170:173], v[194:197], v[104:107]
	v_mfma_f32_16x16x32_bf16 v[96:99], v[178:181], v[194:197], v[96:99]
	v_mfma_f32_16x16x32_bf16 v[88:91], v[170:173], v[202:205], v[88:91]
	v_mfma_f32_16x16x32_bf16 v[80:83], v[178:181], v[202:205], v[80:83]
	v_mfma_f32_16x16x32_bf16 v[72:75], v[170:173], v[210:213], v[72:75]
	v_mfma_f32_16x16x32_bf16 v[64:67], v[178:181], v[210:213], v[64:67]
	v_mfma_f32_16x16x32_bf16 v[124:127], v[174:177], v[190:193], v[124:127]
	v_mfma_f32_16x16x32_bf16 v[120:123], v[182:185], v[190:193], v[120:123]
	v_mfma_f32_16x16x32_bf16 v[104:107], v[174:177], v[198:201], v[104:107]
	v_mfma_f32_16x16x32_bf16 v[96:99], v[182:185], v[198:201], v[96:99]
	v_mfma_f32_16x16x32_bf16 v[88:91], v[174:177], v[206:209], v[88:91]
	v_mfma_f32_16x16x32_bf16 v[80:83], v[182:185], v[206:209], v[80:83]
	v_mfma_f32_16x16x32_bf16 v[72:75], v[174:177], v[214:217], v[72:75]
	v_mfma_f32_16x16x32_bf16 v[64:67], v[182:185], v[214:217], v[64:67]
	s_barrier
	s_setprio 0
	s_add_i32 s34, s64, s36
	v_lshl_add_u64 v[144:145], v[144:145], 0, s[12:13]
	s_mov_b32 m0, s34
	s_nop 0
	global_load_lds_dwordx4 v[144:145], off
	s_add_i32 m0, s34, 0x2000
	s_add_u32 s30, s30, 0x40080
	v_lshl_add_u64 v[144:145], v[218:219], 0, s[12:13]
	s_addc_u32 s31, s31, 0
	s_add_i32 s34, s65, s36
	global_load_lds_dwordx4 v[144:145], off
	v_lshl_add_u64 v[144:145], s[30:31], 0, v[132:133]
	s_mov_b32 m0, s34
	s_nop 0
	global_load_lds_dwordx4 v[144:145], off
	v_lshl_add_u64 v[144:145], s[30:31], 0, v[128:129]
	s_add_i32 m0, s34, 0x2000
	s_nop 0
	global_load_lds_dwordx4 v[144:145], off
	v_lshl_add_u64 v[144:145], v[220:221], 0, s[12:13]
	s_mov_b32 m0, s42
	s_nop 0
	global_load_lds_dwordx4 v[144:145], off
	v_lshl_add_u64 v[144:145], v[222:223], 0, s[12:13]
	s_mov_b32 m0, s43
	s_nop 0
	global_load_lds_dwordx4 v[144:145], off
	ds_read_b128 v[186:189], v151 offset:49152
	ds_read_b128 v[190:193], v151 offset:50176
	ds_read_b128 v[194:197], v151 offset:51200
	ds_read_b128 v[198:201], v151 offset:52224
	ds_read_b128 v[202:205], v151 offset:53248
	ds_read_b128 v[206:209], v151 offset:54272
	ds_read_b128 v[210:213], v151 offset:55296
	ds_read_b128 v[214:217], v151 offset:56320
	s_waitcnt vmcnt(8)
	s_waitcnt lgkmcnt(0)
	s_setprio 1
	s_barrier
	v_mfma_f32_16x16x32_bf16 v[60:63], v[154:157], v[186:189], v[60:63]
	v_mfma_f32_16x16x32_bf16 v[52:55], v[162:165], v[186:189], v[52:55]
	v_mfma_f32_16x16x32_bf16 v[44:47], v[154:157], v[194:197], v[44:47]
	v_mfma_f32_16x16x32_bf16 v[36:39], v[162:165], v[194:197], v[36:39]
	v_mfma_f32_16x16x32_bf16 v[28:31], v[154:157], v[202:205], v[28:31]
	v_mfma_f32_16x16x32_bf16 v[20:23], v[162:165], v[202:205], v[20:23]
	v_mfma_f32_16x16x32_bf16 v[12:15], v[154:157], v[210:213], v[12:15]
	v_mfma_f32_16x16x32_bf16 v[4:7], v[162:165], v[210:213], v[4:7]
	v_mfma_f32_16x16x32_bf16 v[60:63], v[158:161], v[190:193], v[60:63]
	v_mfma_f32_16x16x32_bf16 v[52:55], v[166:169], v[190:193], v[52:55]
	v_mfma_f32_16x16x32_bf16 v[44:47], v[158:161], v[198:201], v[44:47]
	v_mfma_f32_16x16x32_bf16 v[36:39], v[166:169], v[198:201], v[36:39]
	v_mfma_f32_16x16x32_bf16 v[28:31], v[158:161], v[206:209], v[28:31]
	v_mfma_f32_16x16x32_bf16 v[20:23], v[166:169], v[206:209], v[20:23]
	v_mfma_f32_16x16x32_bf16 v[12:15], v[158:161], v[214:217], v[12:15]
	v_mfma_f32_16x16x32_bf16 v[4:7], v[166:169], v[214:217], v[4:7]
	s_setprio 0
	s_setprio 1
	v_mfma_f32_16x16x32_bf16 v[56:59], v[170:173], v[186:189], v[56:59]
	v_mfma_f32_16x16x32_bf16 v[48:51], v[178:181], v[186:189], v[48:51]
	v_mfma_f32_16x16x32_bf16 v[40:43], v[170:173], v[194:197], v[40:43]
	v_mfma_f32_16x16x32_bf16 v[32:35], v[178:181], v[194:197], v[32:35]
	v_mfma_f32_16x16x32_bf16 v[24:27], v[170:173], v[202:205], v[24:27]
	v_mfma_f32_16x16x32_bf16 v[16:19], v[178:181], v[202:205], v[16:19]
	v_mfma_f32_16x16x32_bf16 v[8:11], v[170:173], v[210:213], v[8:11]
	v_mfma_f32_16x16x32_bf16 v[0:3], v[178:181], v[210:213], v[0:3]
	v_mfma_f32_16x16x32_bf16 v[56:59], v[174:177], v[190:193], v[56:59]
	v_mfma_f32_16x16x32_bf16 v[48:51], v[182:185], v[190:193], v[48:51]
	v_mfma_f32_16x16x32_bf16 v[40:43], v[174:177], v[198:201], v[40:43]
	v_mfma_f32_16x16x32_bf16 v[32:35], v[182:185], v[198:201], v[32:35]
	v_mfma_f32_16x16x32_bf16 v[24:27], v[174:177], v[206:209], v[24:27]
	v_mfma_f32_16x16x32_bf16 v[16:19], v[182:185], v[206:209], v[16:19]
	v_mfma_f32_16x16x32_bf16 v[8:11], v[174:177], v[214:217], v[8:11]
	v_mfma_f32_16x16x32_bf16 v[0:3], v[182:185], v[214:217], v[0:3]
	s_barrier
	s_setprio 0
	s_add_i32 s63, s63, 2
	s_add_u32 s28, s28, 0x100
	s_addc_u32 s29, s29, 0
	s_add_u32 s61, s61, 0x100
	s_addc_u32 s62, s62, 0
	s_cmp_gt_u32 s63, 13
	s_cbranch_scc0 .LBB0_555
	s_and_b64 vcc, exec, s[14:15]
	s_cbranch_vccz .LBB0_558
	s_barrier

.LBB0_637:
	s_add_u32 s22, s20, 0x100
	s_addc_u32 s23, s21, 0
	s_cmp_eq_u32 s61, 40
	s_cselect_b32 s27, s9, s23
	s_cselect_b32 s26, s8, s22
	s_cselect_b32 s25, s19, s60
	s_cselect_b32 s24, s18, s51
	v_lshl_add_u64 v[206:207], s[20:21], 0, v[200:201]
	s_add_i32 m0, s29, 0xc000
	s_nop 0
	global_load_lds_dwordx4 v[206:207], off
	v_lshl_add_u64 v[206:207], s[20:21], 0, v[202:203]
	s_add_i32 m0, s29, 0xe000
	s_nop 0
	global_load_lds_dwordx4 v[206:207], off
	ds_read_b128 v[120:123], v247
	ds_read_b128 v[124:127], v247 offset:1024
	ds_read_b128 v[128:131], v247 offset:2048
	ds_read_b128 v[132:135], v247 offset:3072
	ds_read_b128 v[140:143], v248
	ds_read_b128 v[148:151], v248 offset:1024
	ds_read_b128 v[152:155], v248 offset:2048
	ds_read_b128 v[156:159], v248 offset:3072
	ds_read_b128 v[160:163], v249
	ds_read_b128 v[164:167], v249 offset:1024
	ds_read_b128 v[168:171], v249 offset:2048
	ds_read_b128 v[172:175], v249 offset:3072
	ds_read_b128 v[176:179], v249 offset:4096
	ds_read_b128 v[180:183], v249 offset:5120
	ds_read_b128 v[184:187], v249 offset:6144
	ds_read_b128 v[188:191], v249 offset:7168
	s_waitcnt vmcnt(8)
	s_waitcnt lgkmcnt(0)
	s_setprio 1
	s_barrier
	v_mfma_f32_16x16x32_bf16 v[144:147], v[120:123], v[160:163], v[144:147]
	v_mfma_f32_16x16x32_bf16 v[136:139], v[128:131], v[160:163], v[136:139]
	v_mfma_f32_16x16x32_bf16 v[108:111], v[120:123], v[168:171], v[108:111]
	v_mfma_f32_16x16x32_bf16 v[104:107], v[128:131], v[168:171], v[104:107]
	v_mfma_f32_16x16x32_bf16 v[92:95], v[120:123], v[176:179], v[92:95]
	v_mfma_f32_16x16x32_bf16 v[88:91], v[128:131], v[176:179], v[88:91]
	v_mfma_f32_16x16x32_bf16 v[76:79], v[120:123], v[184:187], v[76:79]
	v_mfma_f32_16x16x32_bf16 v[72:75], v[128:131], v[184:187], v[72:75]
	v_mfma_f32_16x16x32_bf16 v[144:147], v[124:127], v[164:167], v[144:147]
	v_mfma_f32_16x16x32_bf16 v[136:139], v[132:135], v[164:167], v[136:139]
	v_mfma_f32_16x16x32_bf16 v[108:111], v[124:127], v[172:175], v[108:111]
	v_mfma_f32_16x16x32_bf16 v[104:107], v[132:135], v[172:175], v[104:107]
	v_mfma_f32_16x16x32_bf16 v[92:95], v[124:127], v[180:183], v[92:95]
	v_mfma_f32_16x16x32_bf16 v[88:91], v[132:135], v[180:183], v[88:91]
	v_mfma_f32_16x16x32_bf16 v[76:79], v[124:127], v[188:191], v[76:79]
	v_mfma_f32_16x16x32_bf16 v[72:75], v[132:135], v[188:191], v[72:75]
	s_setprio 0
	s_setprio 1
	v_mfma_f32_16x16x32_bf16 v[116:119], v[140:143], v[160:163], v[116:119]
	v_mfma_f32_16x16x32_bf16 v[112:115], v[152:155], v[160:163], v[112:115]
	v_mfma_f32_16x16x32_bf16 v[100:103], v[140:143], v[168:171], v[100:103]
	v_mfma_f32_16x16x32_bf16 v[96:99], v[152:155], v[168:171], v[96:99]
	v_mfma_f32_16x16x32_bf16 v[84:87], v[140:143], v[176:179], v[84:87]
	v_mfma_f32_16x16x32_bf16 v[80:83], v[152:155], v[176:179], v[80:83]
	v_mfma_f32_16x16x32_bf16 v[68:71], v[140:143], v[184:187], v[68:71]
	v_mfma_f32_16x16x32_bf16 v[64:67], v[152:155], v[184:187], v[64:67]
	v_mfma_f32_16x16x32_bf16 v[116:119], v[148:151], v[164:167], v[116:119]
	v_mfma_f32_16x16x32_bf16 v[112:115], v[156:159], v[164:167], v[112:115]
	v_mfma_f32_16x16x32_bf16 v[100:103], v[148:151], v[172:175], v[100:103]
	v_mfma_f32_16x16x32_bf16 v[96:99], v[156:159], v[172:175], v[96:99]
	v_mfma_f32_16x16x32_bf16 v[84:87], v[148:151], v[180:183], v[84:87]
	v_mfma_f32_16x16x32_bf16 v[80:83], v[156:159], v[180:183], v[80:83]
	v_mfma_f32_16x16x32_bf16 v[68:71], v[148:151], v[188:191], v[68:71]
	v_mfma_f32_16x16x32_bf16 v[64:67], v[156:159], v[188:191], v[64:67]
	s_barrier
	s_setprio 0
	s_add_i32 s20, s43, s28
	v_lshl_add_u64 v[206:207], s[24:25], 0, v[194:195]
	s_mov_b32 m0, s20
	s_nop 0
	global_load_lds_dwordx4 v[206:207], off
	s_add_i32 m0, s20, 0x2000
	s_add_u32 s20, s24, 0xb0000
	v_lshl_add_u64 v[208:209], s[24:25], 0, v[198:199]
	s_addc_u32 s21, s25, 0
	s_add_i32 s62, s46, s28
	global_load_lds_dwordx4 v[208:209], off
	v_lshl_add_u64 v[210:211], s[20:21], 0, v[194:195]
	s_mov_b32 m0, s62
	v_lshl_add_u64 v[212:213], s[26:27], 0, v[196:197]
	global_load_lds_dwordx4 v[210:211], off
	v_lshl_add_u64 v[210:211], s[20:21], 0, v[198:199]
	s_add_i32 m0, s62, 0x2000
	s_nop 0
	global_load_lds_dwordx4 v[210:211], off
	v_lshl_add_u64 v[210:211], s[26:27], 0, v[192:193]
	s_mov_b32 m0, s29
	s_nop 0
	global_load_lds_dwordx4 v[210:211], off
	s_mov_b32 m0, s30
	s_nop 0
	global_load_lds_dwordx4 v[212:213], off
	ds_read_b128 v[160:163], v249 offset:16384
	ds_read_b128 v[164:167], v249 offset:17408
	ds_read_b128 v[168:171], v249 offset:18432
	ds_read_b128 v[172:175], v249 offset:19456
	ds_read_b128 v[176:179], v249 offset:20480
	ds_read_b128 v[180:183], v249 offset:21504
	ds_read_b128 v[184:187], v249 offset:22528
	ds_read_b128 v[188:191], v249 offset:23552
	s_waitcnt vmcnt(8)
	s_waitcnt lgkmcnt(0)
	s_setprio 1
	s_barrier
	v_mfma_f32_16x16x32_bf16 v[60:63], v[120:123], v[160:163], v[60:63]
	v_mfma_f32_16x16x32_bf16 v[56:59], v[128:131], v[160:163], v[56:59]
	v_mfma_f32_16x16x32_bf16 v[44:47], v[120:123], v[168:171], v[44:47]
	v_mfma_f32_16x16x32_bf16 v[40:43], v[128:131], v[168:171], v[40:43]
	v_mfma_f32_16x16x32_bf16 v[28:31], v[120:123], v[176:179], v[28:31]
	v_mfma_f32_16x16x32_bf16 v[24:27], v[128:131], v[176:179], v[24:27]
	v_mfma_f32_16x16x32_bf16 v[12:15], v[120:123], v[184:187], v[12:15]
	v_mfma_f32_16x16x32_bf16 v[8:11], v[128:131], v[184:187], v[8:11]
	v_mfma_f32_16x16x32_bf16 v[60:63], v[124:127], v[164:167], v[60:63]
	v_mfma_f32_16x16x32_bf16 v[56:59], v[132:135], v[164:167], v[56:59]
	v_mfma_f32_16x16x32_bf16 v[44:47], v[124:127], v[172:175], v[44:47]
	v_mfma_f32_16x16x32_bf16 v[40:43], v[132:135], v[172:175], v[40:43]
	v_mfma_f32_16x16x32_bf16 v[28:31], v[124:127], v[180:183], v[28:31]
	v_mfma_f32_16x16x32_bf16 v[24:27], v[132:135], v[180:183], v[24:27]
	v_mfma_f32_16x16x32_bf16 v[12:15], v[124:127], v[188:191], v[12:15]
	v_mfma_f32_16x16x32_bf16 v[8:11], v[132:135], v[188:191], v[8:11]
	s_setprio 0
	s_setprio 1
	v_mfma_f32_16x16x32_bf16 v[52:55], v[140:143], v[160:163], v[52:55]
	v_mfma_f32_16x16x32_bf16 v[48:51], v[152:155], v[160:163], v[48:51]
	v_mfma_f32_16x16x32_bf16 v[36:39], v[140:143], v[168:171], v[36:39]
	v_mfma_f32_16x16x32_bf16 v[32:35], v[152:155], v[168:171], v[32:35]
	v_mfma_f32_16x16x32_bf16 v[20:23], v[140:143], v[176:179], v[20:23]
	v_mfma_f32_16x16x32_bf16 v[16:19], v[152:155], v[176:179], v[16:19]
	v_mfma_f32_16x16x32_bf16 v[4:7], v[140:143], v[184:187], v[4:7]
	v_mfma_f32_16x16x32_bf16 v[0:3], v[152:155], v[184:187], v[0:3]
	v_mfma_f32_16x16x32_bf16 v[52:55], v[148:151], v[164:167], v[52:55]
	v_mfma_f32_16x16x32_bf16 v[48:51], v[156:159], v[164:167], v[48:51]
	v_mfma_f32_16x16x32_bf16 v[36:39], v[148:151], v[172:175], v[36:39]
	v_mfma_f32_16x16x32_bf16 v[32:35], v[156:159], v[172:175], v[32:35]
	v_mfma_f32_16x16x32_bf16 v[20:23], v[148:151], v[180:183], v[20:23]
	v_mfma_f32_16x16x32_bf16 v[16:19], v[156:159], v[180:183], v[16:19]
	v_mfma_f32_16x16x32_bf16 v[4:7], v[148:151], v[188:191], v[4:7]
	v_mfma_f32_16x16x32_bf16 v[0:3], v[156:159], v[188:191], v[0:3]
	s_barrier
	s_setprio 0
	s_add_i32 s62, 0, 0x18000
	s_add_i32 s63, 0, 0x1c000
	s_add_u32 s20, s26, 0xb0000
	s_addc_u32 s21, s27, 0
	s_mov_b32 m0, s31
	v_lshl_add_u64 v[214:215], s[20:21], 0, v[192:193]
	global_load_lds_dwordx4 v[214:215], off
	v_lshl_add_u64 v[214:215], s[20:21], 0, v[196:197]
	s_mov_b32 m0, s34
	s_nop 0
	global_load_lds_dwordx4 v[214:215], off
	v_add_u32_e32 v132, s62, v246
	v_add_u32_e32 v156, s63, v246
	ds_read_b128 v[120:123], v132
	ds_read_b128 v[124:127], v132 offset:1024
	ds_read_b128 v[128:131], v132 offset:2048
	ds_read_b128 v[132:135], v132 offset:3072
	ds_read_b128 v[140:143], v156
	ds_read_b128 v[148:151], v156 offset:1024
	ds_read_b128 v[152:155], v156 offset:2048
	ds_read_b128 v[156:159], v156 offset:3072
	ds_read_b128 v[160:163], v249 offset:32768
	ds_read_b128 v[164:167], v249 offset:33792
	ds_read_b128 v[168:171], v249 offset:34816
	ds_read_b128 v[172:175], v249 offset:35840
	ds_read_b128 v[176:179], v249 offset:36864
	ds_read_b128 v[180:183], v249 offset:37888
	ds_read_b128 v[184:187], v249 offset:38912
	ds_read_b128 v[188:191], v249 offset:39936
	s_waitcnt vmcnt(8)
	s_waitcnt lgkmcnt(0)
	s_setprio 1
	s_barrier
	v_mfma_f32_16x16x32_bf16 v[144:147], v[120:123], v[160:163], v[144:147]
	v_mfma_f32_16x16x32_bf16 v[136:139], v[128:131], v[160:163], v[136:139]
	v_mfma_f32_16x16x32_bf16 v[108:111], v[120:123], v[168:171], v[108:111]
	v_mfma_f32_16x16x32_bf16 v[104:107], v[128:131], v[168:171], v[104:107]
	v_mfma_f32_16x16x32_bf16 v[92:95], v[120:123], v[176:179], v[92:95]
	v_mfma_f32_16x16x32_bf16 v[88:91], v[128:131], v[176:179], v[88:91]
	v_mfma_f32_16x16x32_bf16 v[76:79], v[120:123], v[184:187], v[76:79]
	v_mfma_f32_16x16x32_bf16 v[72:75], v[128:131], v[184:187], v[72:75]
	v_mfma_f32_16x16x32_bf16 v[144:147], v[124:127], v[164:167], v[144:147]
	v_mfma_f32_16x16x32_bf16 v[136:139], v[132:135], v[164:167], v[136:139]
	v_mfma_f32_16x16x32_bf16 v[108:111], v[124:127], v[172:175], v[108:111]
	v_mfma_f32_16x16x32_bf16 v[104:107], v[132:135], v[172:175], v[104:107]
	v_mfma_f32_16x16x32_bf16 v[92:95], v[124:127], v[180:183], v[92:95]
	v_mfma_f32_16x16x32_bf16 v[88:91], v[132:135], v[180:183], v[88:91]
	v_mfma_f32_16x16x32_bf16 v[76:79], v[124:127], v[188:191], v[76:79]
	v_mfma_f32_16x16x32_bf16 v[72:75], v[132:135], v[188:191], v[72:75]
	s_setprio 0
	s_setprio 1
	v_mfma_f32_16x16x32_bf16 v[116:119], v[140:143], v[160:163], v[116:119]
	v_mfma_f32_16x16x32_bf16 v[112:115], v[152:155], v[160:163], v[112:115]
	v_mfma_f32_16x16x32_bf16 v[100:103], v[140:143], v[168:171], v[100:103]
	v_mfma_f32_16x16x32_bf16 v[96:99], v[152:155], v[168:171], v[96:99]
	v_mfma_f32_16x16x32_bf16 v[84:87], v[140:143], v[176:179], v[84:87]
	v_mfma_f32_16x16x32_bf16 v[80:83], v[152:155], v[176:179], v[80:83]
	v_mfma_f32_16x16x32_bf16 v[68:71], v[140:143], v[184:187], v[68:71]
	v_mfma_f32_16x16x32_bf16 v[64:67], v[152:155], v[184:187], v[64:67]
	v_mfma_f32_16x16x32_bf16 v[116:119], v[148:151], v[164:167], v[116:119]
	v_mfma_f32_16x16x32_bf16 v[112:115], v[156:159], v[164:167], v[112:115]
	v_mfma_f32_16x16x32_bf16 v[100:103], v[148:151], v[172:175], v[100:103]
	v_mfma_f32_16x16x32_bf16 v[96:99], v[156:159], v[172:175], v[96:99]
	v_mfma_f32_16x16x32_bf16 v[84:87], v[148:151], v[180:183], v[84:87]
	v_mfma_f32_16x16x32_bf16 v[80:83], v[156:159], v[180:183], v[80:83]
	v_mfma_f32_16x16x32_bf16 v[68:71], v[148:151], v[188:191], v[68:71]
	v_mfma_f32_16x16x32_bf16 v[64:67], v[156:159], v[188:191], v[64:67]
	s_barrier
	s_setprio 0
	s_add_i32 s20, s62, s28
	v_lshl_add_u64 v[206:207], v[206:207], 0, s[14:15]
	s_mov_b32 m0, s20
	s_nop 0
	global_load_lds_dwordx4 v[206:207], off
	s_add_i32 m0, s20, 0x2000
	s_add_u32 s20, s24, 0xb0080
	v_lshl_add_u64 v[206:207], v[208:209], 0, s[14:15]
	s_addc_u32 s21, s25, 0
	s_add_i32 s24, s63, s28
	global_load_lds_dwordx4 v[206:207], off
	v_lshl_add_u64 v[206:207], s[20:21], 0, v[194:195]
	s_mov_b32 m0, s24
	s_nop 0
	global_load_lds_dwordx4 v[206:207], off
	v_lshl_add_u64 v[206:207], s[20:21], 0, v[198:199]
	s_add_i32 m0, s24, 0x2000
	s_nop 0
	global_load_lds_dwordx4 v[206:207], off
	v_lshl_add_u64 v[206:207], v[210:211], 0, s[14:15]
	s_mov_b32 m0, s38
	s_nop 0
	global_load_lds_dwordx4 v[206:207], off
	v_lshl_add_u64 v[206:207], v[212:213], 0, s[14:15]
	s_mov_b32 m0, s39
	s_nop 0
	global_load_lds_dwordx4 v[206:207], off
	ds_read_b128 v[160:163], v249 offset:49152
	ds_read_b128 v[164:167], v249 offset:50176
	ds_read_b128 v[168:171], v249 offset:51200
	ds_read_b128 v[172:175], v249 offset:52224
	ds_read_b128 v[176:179], v249 offset:53248
	ds_read_b128 v[180:183], v249 offset:54272
	ds_read_b128 v[184:187], v249 offset:55296
	ds_read_b128 v[188:191], v249 offset:56320
	s_waitcnt vmcnt(8)
	s_waitcnt lgkmcnt(0)
	s_setprio 1
	s_barrier
	v_mfma_f32_16x16x32_bf16 v[60:63], v[120:123], v[160:163], v[60:63]
	v_mfma_f32_16x16x32_bf16 v[56:59], v[128:131], v[160:163], v[56:59]
	v_mfma_f32_16x16x32_bf16 v[44:47], v[120:123], v[168:171], v[44:47]
	v_mfma_f32_16x16x32_bf16 v[40:43], v[128:131], v[168:171], v[40:43]
	v_mfma_f32_16x16x32_bf16 v[28:31], v[120:123], v[176:179], v[28:31]
	v_mfma_f32_16x16x32_bf16 v[24:27], v[128:131], v[176:179], v[24:27]
	v_mfma_f32_16x16x32_bf16 v[12:15], v[120:123], v[184:187], v[12:15]
	v_mfma_f32_16x16x32_bf16 v[8:11], v[128:131], v[184:187], v[8:11]
	v_mfma_f32_16x16x32_bf16 v[60:63], v[124:127], v[164:167], v[60:63]
	v_mfma_f32_16x16x32_bf16 v[56:59], v[132:135], v[164:167], v[56:59]
	v_mfma_f32_16x16x32_bf16 v[44:47], v[124:127], v[172:175], v[44:47]
	v_mfma_f32_16x16x32_bf16 v[40:43], v[132:135], v[172:175], v[40:43]
	v_mfma_f32_16x16x32_bf16 v[28:31], v[124:127], v[180:183], v[28:31]
	v_mfma_f32_16x16x32_bf16 v[24:27], v[132:135], v[180:183], v[24:27]
	v_mfma_f32_16x16x32_bf16 v[12:15], v[124:127], v[188:191], v[12:15]
	v_mfma_f32_16x16x32_bf16 v[8:11], v[132:135], v[188:191], v[8:11]
	s_setprio 0
	s_setprio 1
	v_mfma_f32_16x16x32_bf16 v[52:55], v[140:143], v[160:163], v[52:55]
	v_mfma_f32_16x16x32_bf16 v[48:51], v[152:155], v[160:163], v[48:51]
	v_mfma_f32_16x16x32_bf16 v[36:39], v[140:143], v[168:171], v[36:39]
	v_mfma_f32_16x16x32_bf16 v[32:35], v[152:155], v[168:171], v[32:35]
	v_mfma_f32_16x16x32_bf16 v[20:23], v[140:143], v[176:179], v[20:23]
	v_mfma_f32_16x16x32_bf16 v[16:19], v[152:155], v[176:179], v[16:19]
	v_mfma_f32_16x16x32_bf16 v[4:7], v[140:143], v[184:187], v[4:7]
	v_mfma_f32_16x16x32_bf16 v[0:3], v[152:155], v[184:187], v[0:3]
	v_mfma_f32_16x16x32_bf16 v[52:55], v[148:151], v[164:167], v[52:55]
	v_mfma_f32_16x16x32_bf16 v[48:51], v[156:159], v[164:167], v[48:51]
	v_mfma_f32_16x16x32_bf16 v[36:39], v[148:151], v[172:175], v[36:39]
	v_mfma_f32_16x16x32_bf16 v[32:35], v[156:159], v[172:175], v[32:35]
	v_mfma_f32_16x16x32_bf16 v[20:23], v[148:151], v[180:183], v[20:23]
	v_mfma_f32_16x16x32_bf16 v[16:19], v[156:159], v[180:183], v[16:19]
	v_mfma_f32_16x16x32_bf16 v[4:7], v[148:151], v[188:191], v[4:7]
	v_mfma_f32_16x16x32_bf16 v[0:3], v[156:159], v[188:191], v[0:3]
	s_barrier
	s_setprio 0
	s_add_i32 s61, s61, 2
	s_add_u32 s51, s51, 0x100
	s_addc_u32 s60, s60, 0
	s_cmp_gt_u32 s61, 41
	s_mov_b64 s[20:21], s[22:23]
	s_cbranch_scc0 .LBB0_637
	s_and_b64 vcc, exec, s[16:17]
	s_cbranch_vccz .LBB0_640
	s_barrier

.LBB0_723:
	s_add_u32 s62, s48, 0xfffc0080
	s_addc_u32 s63, s49, -1
	s_cmp_eq_u32 s93, 12
	s_cselect_b32 s65, s9, s63
	s_cselect_b32 s64, s41, s62
	s_cselect_b32 s63, s39, s61
	s_cselect_b32 s62, s51, s60
	v_lshl_add_u64 v[192:193], s[48:49], 0, v[214:215]
	s_add_i32 m0, s69, 0xc000
	s_nop 0
	global_load_lds_dwordx4 v[192:193], off
	v_lshl_add_u64 v[192:193], s[48:49], 0, v[216:217]
	s_add_i32 m0, s69, 0xe000
	s_nop 0
	global_load_lds_dwordx4 v[192:193], off
	ds_read_b128 v[128:131], v235
	ds_read_b128 v[132:135], v235 offset:1024
	ds_read_b128 v[136:139], v235 offset:2048
	ds_read_b128 v[140:143], v235 offset:3072
	ds_read_b128 v[144:147], v236
	ds_read_b128 v[148:151], v236 offset:1024
	ds_read_b128 v[152:155], v236 offset:2048
	ds_read_b128 v[156:159], v236 offset:3072
	ds_read_b128 v[160:163], v237
	ds_read_b128 v[164:167], v237 offset:1024
	ds_read_b128 v[168:171], v237 offset:2048
	ds_read_b128 v[172:175], v237 offset:3072
	ds_read_b128 v[176:179], v237 offset:4096
	ds_read_b128 v[180:183], v237 offset:5120
	ds_read_b128 v[184:187], v237 offset:6144
	ds_read_b128 v[188:191], v237 offset:7168
	s_waitcnt vmcnt(8)
	s_waitcnt lgkmcnt(0)
	s_setprio 1
	s_barrier
	v_mfma_f32_16x16x32_bf16 v[124:127], v[128:131], v[160:163], v[124:127]
	v_mfma_f32_16x16x32_bf16 v[120:123], v[136:139], v[160:163], v[120:123]
	v_mfma_f32_16x16x32_bf16 v[116:119], v[128:131], v[168:171], v[116:119]
	v_mfma_f32_16x16x32_bf16 v[112:115], v[136:139], v[168:171], v[112:115]
	v_mfma_f32_16x16x32_bf16 v[108:111], v[128:131], v[176:179], v[108:111]
	v_mfma_f32_16x16x32_bf16 v[100:103], v[136:139], v[176:179], v[100:103]
	v_mfma_f32_16x16x32_bf16 v[92:95], v[128:131], v[184:187], v[92:95]
	v_mfma_f32_16x16x32_bf16 v[80:83], v[136:139], v[184:187], v[80:83]
	v_mfma_f32_16x16x32_bf16 v[124:127], v[132:135], v[164:167], v[124:127]
	v_mfma_f32_16x16x32_bf16 v[120:123], v[140:143], v[164:167], v[120:123]
	v_mfma_f32_16x16x32_bf16 v[116:119], v[132:135], v[172:175], v[116:119]
	v_mfma_f32_16x16x32_bf16 v[112:115], v[140:143], v[172:175], v[112:115]
	v_mfma_f32_16x16x32_bf16 v[108:111], v[132:135], v[180:183], v[108:111]
	v_mfma_f32_16x16x32_bf16 v[100:103], v[140:143], v[180:183], v[100:103]
	v_mfma_f32_16x16x32_bf16 v[92:95], v[132:135], v[188:191], v[92:95]
	v_mfma_f32_16x16x32_bf16 v[80:83], v[140:143], v[188:191], v[80:83]
	s_setprio 0
	s_setprio 1
	v_mfma_f32_16x16x32_bf16 v[104:107], v[144:147], v[160:163], v[104:107]
	v_mfma_f32_16x16x32_bf16 v[96:99], v[152:155], v[160:163], v[96:99]
	v_mfma_f32_16x16x32_bf16 v[88:91], v[144:147], v[168:171], v[88:91]
	v_mfma_f32_16x16x32_bf16 v[84:87], v[152:155], v[168:171], v[84:87]
	v_mfma_f32_16x16x32_bf16 v[76:79], v[144:147], v[176:179], v[76:79]
	v_mfma_f32_16x16x32_bf16 v[72:75], v[152:155], v[176:179], v[72:75]
	v_mfma_f32_16x16x32_bf16 v[68:71], v[144:147], v[184:187], v[68:71]
	v_mfma_f32_16x16x32_bf16 v[64:67], v[152:155], v[184:187], v[64:67]
	v_mfma_f32_16x16x32_bf16 v[104:107], v[148:151], v[164:167], v[104:107]
	v_mfma_f32_16x16x32_bf16 v[96:99], v[156:159], v[164:167], v[96:99]
	v_mfma_f32_16x16x32_bf16 v[88:91], v[148:151], v[172:175], v[88:91]
	v_mfma_f32_16x16x32_bf16 v[84:87], v[156:159], v[172:175], v[84:87]
	v_mfma_f32_16x16x32_bf16 v[76:79], v[148:151], v[180:183], v[76:79]
	v_mfma_f32_16x16x32_bf16 v[72:75], v[156:159], v[180:183], v[72:75]
	v_mfma_f32_16x16x32_bf16 v[68:71], v[148:151], v[188:191], v[68:71]
	v_mfma_f32_16x16x32_bf16 v[64:67], v[156:159], v[188:191], v[64:67]
	s_barrier
	s_setprio 0
	s_add_i32 s94, s88, s68
	v_lshl_add_u64 v[192:193], s[62:63], 0, v[208:209]
	s_mov_b32 m0, s94
	s_nop 0
	global_load_lds_dwordx4 v[192:193], off
	s_add_i32 m0, s94, 0x2000
	s_add_u32 s94, s62, 0x40000
	v_lshl_add_u64 v[194:195], s[62:63], 0, v[212:213]
	s_addc_u32 s95, s63, 0
	s_add_i32 s96, s89, s68
	global_load_lds_dwordx4 v[194:195], off
	v_lshl_add_u64 v[196:197], s[94:95], 0, v[208:209]
	s_mov_b32 m0, s96
	v_lshl_add_u64 v[198:199], s[64:65], 0, v[210:211]
	global_load_lds_dwordx4 v[196:197], off
	v_lshl_add_u64 v[196:197], s[94:95], 0, v[212:213]
	s_add_i32 m0, s96, 0x2000
	s_nop 0
	global_load_lds_dwordx4 v[196:197], off
	v_lshl_add_u64 v[196:197], s[64:65], 0, v[206:207]
	s_mov_b32 m0, s69
	s_nop 0
	global_load_lds_dwordx4 v[196:197], off
	s_mov_b32 m0, s70
	s_nop 0
	global_load_lds_dwordx4 v[198:199], off
	ds_read_b128 v[160:163], v237 offset:16384
	ds_read_b128 v[164:167], v237 offset:17408
	ds_read_b128 v[168:171], v237 offset:18432
	ds_read_b128 v[172:175], v237 offset:19456
	ds_read_b128 v[176:179], v237 offset:20480
	ds_read_b128 v[180:183], v237 offset:21504
	ds_read_b128 v[184:187], v237 offset:22528
	ds_read_b128 v[188:191], v237 offset:23552
	s_waitcnt vmcnt(8)
	s_waitcnt lgkmcnt(0)
	s_setprio 1
	s_barrier
	v_mfma_f32_16x16x32_bf16 v[60:63], v[128:131], v[160:163], v[60:63]
	v_mfma_f32_16x16x32_bf16 v[56:59], v[136:139], v[160:163], v[56:59]
	v_mfma_f32_16x16x32_bf16 v[48:51], v[128:131], v[168:171], v[48:51]
	v_mfma_f32_16x16x32_bf16 v[40:43], v[136:139], v[168:171], v[40:43]
	v_mfma_f32_16x16x32_bf16 v[32:35], v[128:131], v[176:179], v[32:35]
	v_mfma_f32_16x16x32_bf16 v[24:27], v[136:139], v[176:179], v[24:27]
	v_mfma_f32_16x16x32_bf16 v[16:19], v[128:131], v[184:187], v[16:19]
	v_mfma_f32_16x16x32_bf16 v[8:11], v[136:139], v[184:187], v[8:11]
	v_mfma_f32_16x16x32_bf16 v[60:63], v[132:135], v[164:167], v[60:63]
	v_mfma_f32_16x16x32_bf16 v[56:59], v[140:143], v[164:167], v[56:59]
	v_mfma_f32_16x16x32_bf16 v[48:51], v[132:135], v[172:175], v[48:51]
	v_mfma_f32_16x16x32_bf16 v[40:43], v[140:143], v[172:175], v[40:43]
	v_mfma_f32_16x16x32_bf16 v[32:35], v[132:135], v[180:183], v[32:35]
	v_mfma_f32_16x16x32_bf16 v[24:27], v[140:143], v[180:183], v[24:27]
	v_mfma_f32_16x16x32_bf16 v[16:19], v[132:135], v[188:191], v[16:19]
	v_mfma_f32_16x16x32_bf16 v[8:11], v[140:143], v[188:191], v[8:11]
	s_setprio 0
	s_setprio 1
	v_mfma_f32_16x16x32_bf16 v[52:55], v[144:147], v[160:163], v[52:55]
	v_mfma_f32_16x16x32_bf16 v[44:47], v[152:155], v[160:163], v[44:47]
	v_mfma_f32_16x16x32_bf16 v[36:39], v[144:147], v[168:171], v[36:39]
	v_mfma_f32_16x16x32_bf16 v[28:31], v[152:155], v[168:171], v[28:31]
	v_mfma_f32_16x16x32_bf16 v[20:23], v[144:147], v[176:179], v[20:23]
	v_mfma_f32_16x16x32_bf16 v[12:15], v[152:155], v[176:179], v[12:15]
	v_mfma_f32_16x16x32_bf16 v[4:7], v[144:147], v[184:187], v[4:7]
	v_mfma_f32_16x16x32_bf16 v[0:3], v[152:155], v[184:187], v[0:3]
	v_mfma_f32_16x16x32_bf16 v[52:55], v[148:151], v[164:167], v[52:55]
	v_mfma_f32_16x16x32_bf16 v[44:47], v[156:159], v[164:167], v[44:47]
	v_mfma_f32_16x16x32_bf16 v[36:39], v[148:151], v[172:175], v[36:39]
	v_mfma_f32_16x16x32_bf16 v[28:31], v[156:159], v[172:175], v[28:31]
	v_mfma_f32_16x16x32_bf16 v[20:23], v[148:151], v[180:183], v[20:23]
	v_mfma_f32_16x16x32_bf16 v[12:15], v[156:159], v[180:183], v[12:15]
	v_mfma_f32_16x16x32_bf16 v[4:7], v[148:151], v[188:191], v[4:7]
	v_mfma_f32_16x16x32_bf16 v[0:3], v[156:159], v[188:191], v[0:3]
	s_barrier
	s_setprio 0
	s_add_i32 s94, 0, 0x18000
	s_add_i32 s95, 0, 0x1c000
	s_add_u32 s64, s64, 0x40000
	s_addc_u32 s65, s65, 0
	s_mov_b32 m0, s71
	v_lshl_add_u64 v[200:201], s[64:65], 0, v[206:207]
	global_load_lds_dwordx4 v[200:201], off
	v_lshl_add_u64 v[200:201], s[64:65], 0, v[210:211]
	s_mov_b32 m0, s72
	s_nop 0
	global_load_lds_dwordx4 v[200:201], off
	v_add_u32_e32 v140, s94, v234
	v_add_u32_e32 v156, s95, v234
	ds_read_b128 v[128:131], v140
	ds_read_b128 v[132:135], v140 offset:1024
	ds_read_b128 v[136:139], v140 offset:2048
	ds_read_b128 v[140:143], v140 offset:3072
	ds_read_b128 v[144:147], v156
	ds_read_b128 v[148:151], v156 offset:1024
	ds_read_b128 v[152:155], v156 offset:2048
	ds_read_b128 v[156:159], v156 offset:3072
	ds_read_b128 v[160:163], v237 offset:32768
	ds_read_b128 v[164:167], v237 offset:33792
	ds_read_b128 v[168:171], v237 offset:34816
	ds_read_b128 v[172:175], v237 offset:35840
	ds_read_b128 v[176:179], v237 offset:36864
	ds_read_b128 v[180:183], v237 offset:37888
	ds_read_b128 v[184:187], v237 offset:38912
	ds_read_b128 v[188:191], v237 offset:39936
	s_waitcnt vmcnt(8)
	s_waitcnt lgkmcnt(0)
	s_setprio 1
	s_barrier
	v_mfma_f32_16x16x32_bf16 v[124:127], v[128:131], v[160:163], v[124:127]
	v_mfma_f32_16x16x32_bf16 v[120:123], v[136:139], v[160:163], v[120:123]
	v_mfma_f32_16x16x32_bf16 v[116:119], v[128:131], v[168:171], v[116:119]
	v_mfma_f32_16x16x32_bf16 v[112:115], v[136:139], v[168:171], v[112:115]
	v_mfma_f32_16x16x32_bf16 v[108:111], v[128:131], v[176:179], v[108:111]
	v_mfma_f32_16x16x32_bf16 v[100:103], v[136:139], v[176:179], v[100:103]
	v_mfma_f32_16x16x32_bf16 v[92:95], v[128:131], v[184:187], v[92:95]
	v_mfma_f32_16x16x32_bf16 v[80:83], v[136:139], v[184:187], v[80:83]
	v_mfma_f32_16x16x32_bf16 v[124:127], v[132:135], v[164:167], v[124:127]
	v_mfma_f32_16x16x32_bf16 v[120:123], v[140:143], v[164:167], v[120:123]
	v_mfma_f32_16x16x32_bf16 v[116:119], v[132:135], v[172:175], v[116:119]
	v_mfma_f32_16x16x32_bf16 v[112:115], v[140:143], v[172:175], v[112:115]
	v_mfma_f32_16x16x32_bf16 v[108:111], v[132:135], v[180:183], v[108:111]
	v_mfma_f32_16x16x32_bf16 v[100:103], v[140:143], v[180:183], v[100:103]
	v_mfma_f32_16x16x32_bf16 v[92:95], v[132:135], v[188:191], v[92:95]
	v_mfma_f32_16x16x32_bf16 v[80:83], v[140:143], v[188:191], v[80:83]
	s_setprio 0
	s_setprio 1
	v_mfma_f32_16x16x32_bf16 v[104:107], v[144:147], v[160:163], v[104:107]
	v_mfma_f32_16x16x32_bf16 v[96:99], v[152:155], v[160:163], v[96:99]
	v_mfma_f32_16x16x32_bf16 v[88:91], v[144:147], v[168:171], v[88:91]
	v_mfma_f32_16x16x32_bf16 v[84:87], v[152:155], v[168:171], v[84:87]
	v_mfma_f32_16x16x32_bf16 v[76:79], v[144:147], v[176:179], v[76:79]
	v_mfma_f32_16x16x32_bf16 v[72:75], v[152:155], v[176:179], v[72:75]
	v_mfma_f32_16x16x32_bf16 v[68:71], v[144:147], v[184:187], v[68:71]
	v_mfma_f32_16x16x32_bf16 v[64:67], v[152:155], v[184:187], v[64:67]
	v_mfma_f32_16x16x32_bf16 v[104:107], v[148:151], v[164:167], v[104:107]
	v_mfma_f32_16x16x32_bf16 v[96:99], v[156:159], v[164:167], v[96:99]
	v_mfma_f32_16x16x32_bf16 v[88:91], v[148:151], v[172:175], v[88:91]
	v_mfma_f32_16x16x32_bf16 v[84:87], v[156:159], v[172:175], v[84:87]
	v_mfma_f32_16x16x32_bf16 v[76:79], v[148:151], v[180:183], v[76:79]
	v_mfma_f32_16x16x32_bf16 v[72:75], v[156:159], v[180:183], v[72:75]
	v_mfma_f32_16x16x32_bf16 v[68:71], v[148:151], v[188:191], v[68:71]
	v_mfma_f32_16x16x32_bf16 v[64:67], v[156:159], v[188:191], v[64:67]
	s_barrier
	s_setprio 0
	s_add_i32 s64, s94, s68
	v_lshl_add_u64 v[192:193], v[192:193], 0, s[14:15]
	s_mov_b32 m0, s64
	s_nop 0
	global_load_lds_dwordx4 v[192:193], off
	s_add_i32 m0, s64, 0x2000
	s_add_u32 s62, s62, 0x40080
	v_lshl_add_u64 v[192:193], v[194:195], 0, s[14:15]
	s_addc_u32 s63, s63, 0
	s_add_i32 s64, s95, s68
	global_load_lds_dwordx4 v[192:193], off
	v_lshl_add_u64 v[192:193], s[62:63], 0, v[208:209]
	s_mov_b32 m0, s64
	s_nop 0
	global_load_lds_dwordx4 v[192:193], off
	v_lshl_add_u64 v[192:193], s[62:63], 0, v[212:213]
	s_add_i32 m0, s64, 0x2000
	s_nop 0
	global_load_lds_dwordx4 v[192:193], off
	v_lshl_add_u64 v[192:193], v[196:197], 0, s[14:15]
	s_mov_b32 m0, s76
	s_nop 0
	global_load_lds_dwordx4 v[192:193], off
	v_lshl_add_u64 v[192:193], v[198:199], 0, s[14:15]
	s_mov_b32 m0, s77
	s_nop 0
	global_load_lds_dwordx4 v[192:193], off
	ds_read_b128 v[160:163], v237 offset:49152
	ds_read_b128 v[164:167], v237 offset:50176
	ds_read_b128 v[168:171], v237 offset:51200
	ds_read_b128 v[172:175], v237 offset:52224
	ds_read_b128 v[176:179], v237 offset:53248
	ds_read_b128 v[180:183], v237 offset:54272
	ds_read_b128 v[184:187], v237 offset:55296
	ds_read_b128 v[188:191], v237 offset:56320
	s_waitcnt vmcnt(8)
	s_waitcnt lgkmcnt(0)
	s_setprio 1
	s_barrier
	v_mfma_f32_16x16x32_bf16 v[60:63], v[128:131], v[160:163], v[60:63]
	v_mfma_f32_16x16x32_bf16 v[56:59], v[136:139], v[160:163], v[56:59]
	v_mfma_f32_16x16x32_bf16 v[48:51], v[128:131], v[168:171], v[48:51]
	v_mfma_f32_16x16x32_bf16 v[40:43], v[136:139], v[168:171], v[40:43]
	v_mfma_f32_16x16x32_bf16 v[32:35], v[128:131], v[176:179], v[32:35]
	v_mfma_f32_16x16x32_bf16 v[24:27], v[136:139], v[176:179], v[24:27]
	v_mfma_f32_16x16x32_bf16 v[16:19], v[128:131], v[184:187], v[16:19]
	v_mfma_f32_16x16x32_bf16 v[8:11], v[136:139], v[184:187], v[8:11]
	v_mfma_f32_16x16x32_bf16 v[60:63], v[132:135], v[164:167], v[60:63]
	v_mfma_f32_16x16x32_bf16 v[56:59], v[140:143], v[164:167], v[56:59]
	v_mfma_f32_16x16x32_bf16 v[48:51], v[132:135], v[172:175], v[48:51]
	v_mfma_f32_16x16x32_bf16 v[40:43], v[140:143], v[172:175], v[40:43]
	v_mfma_f32_16x16x32_bf16 v[32:35], v[132:135], v[180:183], v[32:35]
	v_mfma_f32_16x16x32_bf16 v[24:27], v[140:143], v[180:183], v[24:27]
	v_mfma_f32_16x16x32_bf16 v[16:19], v[132:135], v[188:191], v[16:19]
	v_mfma_f32_16x16x32_bf16 v[8:11], v[140:143], v[188:191], v[8:11]
	s_setprio 0
	s_setprio 1
	v_mfma_f32_16x16x32_bf16 v[52:55], v[144:147], v[160:163], v[52:55]
	v_mfma_f32_16x16x32_bf16 v[44:47], v[152:155], v[160:163], v[44:47]
	v_mfma_f32_16x16x32_bf16 v[36:39], v[144:147], v[168:171], v[36:39]
	v_mfma_f32_16x16x32_bf16 v[28:31], v[152:155], v[168:171], v[28:31]
	v_mfma_f32_16x16x32_bf16 v[20:23], v[144:147], v[176:179], v[20:23]
	v_mfma_f32_16x16x32_bf16 v[12:15], v[152:155], v[176:179], v[12:15]
	v_mfma_f32_16x16x32_bf16 v[4:7], v[144:147], v[184:187], v[4:7]
	v_mfma_f32_16x16x32_bf16 v[0:3], v[152:155], v[184:187], v[0:3]
	v_mfma_f32_16x16x32_bf16 v[52:55], v[148:151], v[164:167], v[52:55]
	v_mfma_f32_16x16x32_bf16 v[44:47], v[156:159], v[164:167], v[44:47]
	v_mfma_f32_16x16x32_bf16 v[36:39], v[148:151], v[172:175], v[36:39]
	v_mfma_f32_16x16x32_bf16 v[28:31], v[156:159], v[172:175], v[28:31]
	v_mfma_f32_16x16x32_bf16 v[20:23], v[148:151], v[180:183], v[20:23]
	v_mfma_f32_16x16x32_bf16 v[12:15], v[156:159], v[180:183], v[12:15]
	v_mfma_f32_16x16x32_bf16 v[4:7], v[148:151], v[188:191], v[4:7]
	v_mfma_f32_16x16x32_bf16 v[0:3], v[156:159], v[188:191], v[0:3]
	s_barrier
	s_setprio 0
	s_add_i32 s93, s93, 2
	s_add_u32 s48, s48, 0x100
	s_addc_u32 s49, s49, 0
	s_add_u32 s60, s60, 0x100
	s_addc_u32 s61, s61, 0
	s_cmp_gt_u32 s93, 13
	s_cbranch_scc0 .LBB0_723
	s_and_b64 vcc, exec, s[16:17]
	s_cbranch_vccz .LBB0_726
	s_barrier

.LBB0_1109:
	s_add_u32 s30, s28, 0xfffc0080
	s_addc_u32 s31, s29, -1
	s_cmp_eq_u32 s64, 12
	s_cselect_b32 s35, s19, s31
	s_cselect_b32 s34, s25, s30
	s_cselect_b32 s31, s17, s63
	s_cselect_b32 s30, s61, s62
	v_lshl_add_u64 v[206:207], s[28:29], 0, v[200:201]
	s_add_i32 m0, s27, 0xc000
	s_nop 0
	global_load_lds_dwordx4 v[206:207], off
	v_lshl_add_u64 v[206:207], s[28:29], 0, v[202:203]
	s_add_i32 m0, s27, 0xe000
	s_nop 0
	global_load_lds_dwordx4 v[206:207], off
	ds_read_b128 v[120:123], v246
	ds_read_b128 v[124:127], v246 offset:1024
	ds_read_b128 v[128:131], v246 offset:2048
	ds_read_b128 v[132:135], v246 offset:3072
	ds_read_b128 v[140:143], v247
	ds_read_b128 v[148:151], v247 offset:1024
	ds_read_b128 v[152:155], v247 offset:2048
	ds_read_b128 v[156:159], v247 offset:3072
	ds_read_b128 v[160:163], v248
	ds_read_b128 v[164:167], v248 offset:1024
	ds_read_b128 v[168:171], v248 offset:2048
	ds_read_b128 v[172:175], v248 offset:3072
	ds_read_b128 v[176:179], v248 offset:4096
	ds_read_b128 v[180:183], v248 offset:5120
	ds_read_b128 v[184:187], v248 offset:6144
	ds_read_b128 v[188:191], v248 offset:7168
	s_waitcnt vmcnt(8)
	s_waitcnt lgkmcnt(0)
	s_setprio 1
	s_barrier
	v_mfma_f32_16x16x32_bf16 v[144:147], v[120:123], v[160:163], v[144:147]
	v_mfma_f32_16x16x32_bf16 v[136:139], v[128:131], v[160:163], v[136:139]
	v_mfma_f32_16x16x32_bf16 v[108:111], v[120:123], v[168:171], v[108:111]
	v_mfma_f32_16x16x32_bf16 v[104:107], v[128:131], v[168:171], v[104:107]
	v_mfma_f32_16x16x32_bf16 v[92:95], v[120:123], v[176:179], v[92:95]
	v_mfma_f32_16x16x32_bf16 v[88:91], v[128:131], v[176:179], v[88:91]
	v_mfma_f32_16x16x32_bf16 v[76:79], v[120:123], v[184:187], v[76:79]
	v_mfma_f32_16x16x32_bf16 v[72:75], v[128:131], v[184:187], v[72:75]
	v_mfma_f32_16x16x32_bf16 v[144:147], v[124:127], v[164:167], v[144:147]
	v_mfma_f32_16x16x32_bf16 v[136:139], v[132:135], v[164:167], v[136:139]
	v_mfma_f32_16x16x32_bf16 v[108:111], v[124:127], v[172:175], v[108:111]
	v_mfma_f32_16x16x32_bf16 v[104:107], v[132:135], v[172:175], v[104:107]
	v_mfma_f32_16x16x32_bf16 v[92:95], v[124:127], v[180:183], v[92:95]
	v_mfma_f32_16x16x32_bf16 v[88:91], v[132:135], v[180:183], v[88:91]
	v_mfma_f32_16x16x32_bf16 v[76:79], v[124:127], v[188:191], v[76:79]
	v_mfma_f32_16x16x32_bf16 v[72:75], v[132:135], v[188:191], v[72:75]
	s_setprio 0
	s_setprio 1
	v_mfma_f32_16x16x32_bf16 v[116:119], v[140:143], v[160:163], v[116:119]
	v_mfma_f32_16x16x32_bf16 v[112:115], v[152:155], v[160:163], v[112:115]
	v_mfma_f32_16x16x32_bf16 v[100:103], v[140:143], v[168:171], v[100:103]
	v_mfma_f32_16x16x32_bf16 v[96:99], v[152:155], v[168:171], v[96:99]
	v_mfma_f32_16x16x32_bf16 v[84:87], v[140:143], v[176:179], v[84:87]
	v_mfma_f32_16x16x32_bf16 v[80:83], v[152:155], v[176:179], v[80:83]
	v_mfma_f32_16x16x32_bf16 v[68:71], v[140:143], v[184:187], v[68:71]
	v_mfma_f32_16x16x32_bf16 v[64:67], v[152:155], v[184:187], v[64:67]
	v_mfma_f32_16x16x32_bf16 v[116:119], v[148:151], v[164:167], v[116:119]
	v_mfma_f32_16x16x32_bf16 v[112:115], v[156:159], v[164:167], v[112:115]
	v_mfma_f32_16x16x32_bf16 v[100:103], v[148:151], v[172:175], v[100:103]
	v_mfma_f32_16x16x32_bf16 v[96:99], v[156:159], v[172:175], v[96:99]
	v_mfma_f32_16x16x32_bf16 v[84:87], v[148:151], v[180:183], v[84:87]
	v_mfma_f32_16x16x32_bf16 v[80:83], v[156:159], v[180:183], v[80:83]
	v_mfma_f32_16x16x32_bf16 v[68:71], v[148:151], v[188:191], v[68:71]
	v_mfma_f32_16x16x32_bf16 v[64:67], v[156:159], v[188:191], v[64:67]
	s_barrier
	s_setprio 0
	s_add_i32 s65, s51, s37
	v_lshl_add_u64 v[206:207], s[30:31], 0, v[194:195]
	s_mov_b32 m0, s65
	s_nop 0
	global_load_lds_dwordx4 v[206:207], off
	s_add_i32 m0, s65, 0x2000
	s_add_u32 s66, s30, 0x40000
	v_lshl_add_u64 v[208:209], s[30:31], 0, v[198:199]
	s_addc_u32 s67, s31, 0
	s_add_i32 s65, s60, s37
	global_load_lds_dwordx4 v[208:209], off
	v_lshl_add_u64 v[210:211], s[66:67], 0, v[194:195]
	s_mov_b32 m0, s65
	v_lshl_add_u64 v[212:213], s[34:35], 0, v[196:197]
	global_load_lds_dwordx4 v[210:211], off
	v_lshl_add_u64 v[210:211], s[66:67], 0, v[198:199]
	s_add_i32 m0, s65, 0x2000
	s_nop 0
	global_load_lds_dwordx4 v[210:211], off
	v_lshl_add_u64 v[210:211], s[34:35], 0, v[192:193]
	s_mov_b32 m0, s27
	s_nop 0
	global_load_lds_dwordx4 v[210:211], off
	s_mov_b32 m0, s38
	s_nop 0
	global_load_lds_dwordx4 v[212:213], off
	ds_read_b128 v[160:163], v248 offset:16384
	ds_read_b128 v[164:167], v248 offset:17408
	ds_read_b128 v[168:171], v248 offset:18432
	ds_read_b128 v[172:175], v248 offset:19456
	ds_read_b128 v[176:179], v248 offset:20480
	ds_read_b128 v[180:183], v248 offset:21504
	ds_read_b128 v[184:187], v248 offset:22528
	ds_read_b128 v[188:191], v248 offset:23552
	s_waitcnt vmcnt(8)
	s_waitcnt lgkmcnt(0)
	s_setprio 1
	s_barrier
	v_mfma_f32_16x16x32_bf16 v[60:63], v[120:123], v[160:163], v[60:63]
	v_mfma_f32_16x16x32_bf16 v[56:59], v[128:131], v[160:163], v[56:59]
	v_mfma_f32_16x16x32_bf16 v[44:47], v[120:123], v[168:171], v[44:47]
	v_mfma_f32_16x16x32_bf16 v[40:43], v[128:131], v[168:171], v[40:43]
	v_mfma_f32_16x16x32_bf16 v[28:31], v[120:123], v[176:179], v[28:31]
	v_mfma_f32_16x16x32_bf16 v[24:27], v[128:131], v[176:179], v[24:27]
	v_mfma_f32_16x16x32_bf16 v[12:15], v[120:123], v[184:187], v[12:15]
	v_mfma_f32_16x16x32_bf16 v[8:11], v[128:131], v[184:187], v[8:11]
	v_mfma_f32_16x16x32_bf16 v[60:63], v[124:127], v[164:167], v[60:63]
	v_mfma_f32_16x16x32_bf16 v[56:59], v[132:135], v[164:167], v[56:59]
	v_mfma_f32_16x16x32_bf16 v[44:47], v[124:127], v[172:175], v[44:47]
	v_mfma_f32_16x16x32_bf16 v[40:43], v[132:135], v[172:175], v[40:43]
	v_mfma_f32_16x16x32_bf16 v[28:31], v[124:127], v[180:183], v[28:31]
	v_mfma_f32_16x16x32_bf16 v[24:27], v[132:135], v[180:183], v[24:27]
	v_mfma_f32_16x16x32_bf16 v[12:15], v[124:127], v[188:191], v[12:15]
	v_mfma_f32_16x16x32_bf16 v[8:11], v[132:135], v[188:191], v[8:11]
	s_setprio 0
	s_setprio 1
	v_mfma_f32_16x16x32_bf16 v[52:55], v[140:143], v[160:163], v[52:55]
	v_mfma_f32_16x16x32_bf16 v[48:51], v[152:155], v[160:163], v[48:51]
	v_mfma_f32_16x16x32_bf16 v[36:39], v[140:143], v[168:171], v[36:39]
	v_mfma_f32_16x16x32_bf16 v[32:35], v[152:155], v[168:171], v[32:35]
	v_mfma_f32_16x16x32_bf16 v[20:23], v[140:143], v[176:179], v[20:23]
	v_mfma_f32_16x16x32_bf16 v[16:19], v[152:155], v[176:179], v[16:19]
	v_mfma_f32_16x16x32_bf16 v[4:7], v[140:143], v[184:187], v[4:7]
	v_mfma_f32_16x16x32_bf16 v[0:3], v[152:155], v[184:187], v[0:3]
	v_mfma_f32_16x16x32_bf16 v[52:55], v[148:151], v[164:167], v[52:55]
	v_mfma_f32_16x16x32_bf16 v[48:51], v[156:159], v[164:167], v[48:51]
	v_mfma_f32_16x16x32_bf16 v[36:39], v[148:151], v[172:175], v[36:39]
	v_mfma_f32_16x16x32_bf16 v[32:35], v[156:159], v[172:175], v[32:35]
	v_mfma_f32_16x16x32_bf16 v[20:23], v[148:151], v[180:183], v[20:23]
	v_mfma_f32_16x16x32_bf16 v[16:19], v[156:159], v[180:183], v[16:19]
	v_mfma_f32_16x16x32_bf16 v[4:7], v[148:151], v[188:191], v[4:7]
	v_mfma_f32_16x16x32_bf16 v[0:3], v[156:159], v[188:191], v[0:3]
	s_barrier
	s_setprio 0
	s_add_i32 s65, 0, 0x18000
	s_add_i32 s66, 0, 0x1c000
	s_add_u32 s34, s34, 0x40000
	s_addc_u32 s35, s35, 0
	s_mov_b32 m0, s39
	v_lshl_add_u64 v[214:215], s[34:35], 0, v[192:193]
	global_load_lds_dwordx4 v[214:215], off
	v_lshl_add_u64 v[214:215], s[34:35], 0, v[196:197]
	s_mov_b32 m0, s40
	s_nop 0
	global_load_lds_dwordx4 v[214:215], off
	v_add_u32_e32 v132, s65, v245
	v_add_u32_e32 v156, s66, v245
	ds_read_b128 v[120:123], v132
	ds_read_b128 v[124:127], v132 offset:1024
	ds_read_b128 v[128:131], v132 offset:2048
	ds_read_b128 v[132:135], v132 offset:3072
	ds_read_b128 v[140:143], v156
	ds_read_b128 v[148:151], v156 offset:1024
	ds_read_b128 v[152:155], v156 offset:2048
	ds_read_b128 v[156:159], v156 offset:3072
	ds_read_b128 v[160:163], v248 offset:32768
	ds_read_b128 v[164:167], v248 offset:33792
	ds_read_b128 v[168:171], v248 offset:34816
	ds_read_b128 v[172:175], v248 offset:35840
	ds_read_b128 v[176:179], v248 offset:36864
	ds_read_b128 v[180:183], v248 offset:37888
	ds_read_b128 v[184:187], v248 offset:38912
	ds_read_b128 v[188:191], v248 offset:39936
	s_waitcnt vmcnt(8)
	s_waitcnt lgkmcnt(0)
	s_setprio 1
	s_barrier
	v_mfma_f32_16x16x32_bf16 v[144:147], v[120:123], v[160:163], v[144:147]
	v_mfma_f32_16x16x32_bf16 v[136:139], v[128:131], v[160:163], v[136:139]
	v_mfma_f32_16x16x32_bf16 v[108:111], v[120:123], v[168:171], v[108:111]
	v_mfma_f32_16x16x32_bf16 v[104:107], v[128:131], v[168:171], v[104:107]
	v_mfma_f32_16x16x32_bf16 v[92:95], v[120:123], v[176:179], v[92:95]
	v_mfma_f32_16x16x32_bf16 v[88:91], v[128:131], v[176:179], v[88:91]
	v_mfma_f32_16x16x32_bf16 v[76:79], v[120:123], v[184:187], v[76:79]
	v_mfma_f32_16x16x32_bf16 v[72:75], v[128:131], v[184:187], v[72:75]
	v_mfma_f32_16x16x32_bf16 v[144:147], v[124:127], v[164:167], v[144:147]
	v_mfma_f32_16x16x32_bf16 v[136:139], v[132:135], v[164:167], v[136:139]
	v_mfma_f32_16x16x32_bf16 v[108:111], v[124:127], v[172:175], v[108:111]
	v_mfma_f32_16x16x32_bf16 v[104:107], v[132:135], v[172:175], v[104:107]
	v_mfma_f32_16x16x32_bf16 v[92:95], v[124:127], v[180:183], v[92:95]
	v_mfma_f32_16x16x32_bf16 v[88:91], v[132:135], v[180:183], v[88:91]
	v_mfma_f32_16x16x32_bf16 v[76:79], v[124:127], v[188:191], v[76:79]
	v_mfma_f32_16x16x32_bf16 v[72:75], v[132:135], v[188:191], v[72:75]
	s_setprio 0
	s_setprio 1
	v_mfma_f32_16x16x32_bf16 v[116:119], v[140:143], v[160:163], v[116:119]
	v_mfma_f32_16x16x32_bf16 v[112:115], v[152:155], v[160:163], v[112:115]
	v_mfma_f32_16x16x32_bf16 v[100:103], v[140:143], v[168:171], v[100:103]
	v_mfma_f32_16x16x32_bf16 v[96:99], v[152:155], v[168:171], v[96:99]
	v_mfma_f32_16x16x32_bf16 v[84:87], v[140:143], v[176:179], v[84:87]
	v_mfma_f32_16x16x32_bf16 v[80:83], v[152:155], v[176:179], v[80:83]
	v_mfma_f32_16x16x32_bf16 v[68:71], v[140:143], v[184:187], v[68:71]
	v_mfma_f32_16x16x32_bf16 v[64:67], v[152:155], v[184:187], v[64:67]
	v_mfma_f32_16x16x32_bf16 v[116:119], v[148:151], v[164:167], v[116:119]
	v_mfma_f32_16x16x32_bf16 v[112:115], v[156:159], v[164:167], v[112:115]
	v_mfma_f32_16x16x32_bf16 v[100:103], v[148:151], v[172:175], v[100:103]
	v_mfma_f32_16x16x32_bf16 v[96:99], v[156:159], v[172:175], v[96:99]
	v_mfma_f32_16x16x32_bf16 v[84:87], v[148:151], v[180:183], v[84:87]
	v_mfma_f32_16x16x32_bf16 v[80:83], v[156:159], v[180:183], v[80:83]
	v_mfma_f32_16x16x32_bf16 v[68:71], v[148:151], v[188:191], v[68:71]
	v_mfma_f32_16x16x32_bf16 v[64:67], v[156:159], v[188:191], v[64:67]
	s_barrier
	s_setprio 0
	s_add_i32 s34, s65, s37
	v_lshl_add_u64 v[206:207], v[206:207], 0, s[12:13]
	s_mov_b32 m0, s34
	s_nop 0
	global_load_lds_dwordx4 v[206:207], off
	s_add_i32 m0, s34, 0x2000
	s_add_u32 s30, s30, 0x40080
	v_lshl_add_u64 v[206:207], v[208:209], 0, s[12:13]
	s_addc_u32 s31, s31, 0
	s_add_i32 s34, s66, s37
	global_load_lds_dwordx4 v[206:207], off
	v_lshl_add_u64 v[206:207], s[30:31], 0, v[194:195]
	s_mov_b32 m0, s34
	s_nop 0
	global_load_lds_dwordx4 v[206:207], off
	v_lshl_add_u64 v[206:207], s[30:31], 0, v[198:199]
	s_add_i32 m0, s34, 0x2000
	s_nop 0
	global_load_lds_dwordx4 v[206:207], off
	v_lshl_add_u64 v[206:207], v[210:211], 0, s[12:13]
	s_mov_b32 m0, s46
	s_nop 0
	global_load_lds_dwordx4 v[206:207], off
	v_lshl_add_u64 v[206:207], v[212:213], 0, s[12:13]
	s_mov_b32 m0, s47
	s_nop 0
	global_load_lds_dwordx4 v[206:207], off
	ds_read_b128 v[160:163], v248 offset:49152
	ds_read_b128 v[164:167], v248 offset:50176
	ds_read_b128 v[168:171], v248 offset:51200
	ds_read_b128 v[172:175], v248 offset:52224
	ds_read_b128 v[176:179], v248 offset:53248
	ds_read_b128 v[180:183], v248 offset:54272
	ds_read_b128 v[184:187], v248 offset:55296
	ds_read_b128 v[188:191], v248 offset:56320
	s_waitcnt vmcnt(8)
	s_waitcnt lgkmcnt(0)
	s_setprio 1
	s_barrier
	v_mfma_f32_16x16x32_bf16 v[60:63], v[120:123], v[160:163], v[60:63]
	v_mfma_f32_16x16x32_bf16 v[56:59], v[128:131], v[160:163], v[56:59]
	v_mfma_f32_16x16x32_bf16 v[44:47], v[120:123], v[168:171], v[44:47]
	v_mfma_f32_16x16x32_bf16 v[40:43], v[128:131], v[168:171], v[40:43]
	v_mfma_f32_16x16x32_bf16 v[28:31], v[120:123], v[176:179], v[28:31]
	v_mfma_f32_16x16x32_bf16 v[24:27], v[128:131], v[176:179], v[24:27]
	v_mfma_f32_16x16x32_bf16 v[12:15], v[120:123], v[184:187], v[12:15]
	v_mfma_f32_16x16x32_bf16 v[8:11], v[128:131], v[184:187], v[8:11]
	v_mfma_f32_16x16x32_bf16 v[60:63], v[124:127], v[164:167], v[60:63]
	v_mfma_f32_16x16x32_bf16 v[56:59], v[132:135], v[164:167], v[56:59]
	v_mfma_f32_16x16x32_bf16 v[44:47], v[124:127], v[172:175], v[44:47]
	v_mfma_f32_16x16x32_bf16 v[40:43], v[132:135], v[172:175], v[40:43]
	v_mfma_f32_16x16x32_bf16 v[28:31], v[124:127], v[180:183], v[28:31]
	v_mfma_f32_16x16x32_bf16 v[24:27], v[132:135], v[180:183], v[24:27]
	v_mfma_f32_16x16x32_bf16 v[12:15], v[124:127], v[188:191], v[12:15]
	v_mfma_f32_16x16x32_bf16 v[8:11], v[132:135], v[188:191], v[8:11]
	s_setprio 0
	s_setprio 1
	v_mfma_f32_16x16x32_bf16 v[52:55], v[140:143], v[160:163], v[52:55]
	v_mfma_f32_16x16x32_bf16 v[48:51], v[152:155], v[160:163], v[48:51]
	v_mfma_f32_16x16x32_bf16 v[36:39], v[140:143], v[168:171], v[36:39]
	v_mfma_f32_16x16x32_bf16 v[32:35], v[152:155], v[168:171], v[32:35]
	v_mfma_f32_16x16x32_bf16 v[20:23], v[140:143], v[176:179], v[20:23]
	v_mfma_f32_16x16x32_bf16 v[16:19], v[152:155], v[176:179], v[16:19]
	v_mfma_f32_16x16x32_bf16 v[4:7], v[140:143], v[184:187], v[4:7]
	v_mfma_f32_16x16x32_bf16 v[0:3], v[152:155], v[184:187], v[0:3]
	v_mfma_f32_16x16x32_bf16 v[52:55], v[148:151], v[164:167], v[52:55]
	v_mfma_f32_16x16x32_bf16 v[48:51], v[156:159], v[164:167], v[48:51]
	v_mfma_f32_16x16x32_bf16 v[36:39], v[148:151], v[172:175], v[36:39]
	v_mfma_f32_16x16x32_bf16 v[32:35], v[156:159], v[172:175], v[32:35]
	v_mfma_f32_16x16x32_bf16 v[20:23], v[148:151], v[180:183], v[20:23]
	v_mfma_f32_16x16x32_bf16 v[16:19], v[156:159], v[180:183], v[16:19]
	v_mfma_f32_16x16x32_bf16 v[4:7], v[148:151], v[188:191], v[4:7]
	v_mfma_f32_16x16x32_bf16 v[0:3], v[156:159], v[188:191], v[0:3]
	s_barrier
	s_setprio 0
	s_add_i32 s64, s64, 2
	s_add_u32 s28, s28, 0x100
	s_addc_u32 s29, s29, 0
	s_add_u32 s62, s62, 0x100
	s_addc_u32 s63, s63, 0
	s_cmp_gt_u32 s64, 13
	s_cbranch_scc0 .LBB0_1109
	s_and_b64 vcc, exec, s[14:15]
	s_cbranch_vccz .LBB0_1112
	s_barrier

.LBB0_1193:
	s_add_u32 s30, s28, 0xfffc0080
	s_addc_u32 s31, s29, -1
	s_cmp_eq_u32 s62, 12
	s_cselect_b32 s35, s19, s31
	s_cselect_b32 s34, s50, s30
	s_cselect_b32 s31, s17, s61
	s_cselect_b32 s30, s51, s60
	v_lshl_add_u64 v[144:145], s[28:29], 0, v[136:137]
	s_add_i32 m0, s25, 0xc000
	s_nop 0
	global_load_lds_dwordx4 v[144:145], off
	v_lshl_add_u64 v[144:145], s[28:29], 0, v[138:139]
	s_add_i32 m0, s25, 0xe000
	s_nop 0
	global_load_lds_dwordx4 v[144:145], off
	ds_read_b128 v[154:157], v149
	ds_read_b128 v[158:161], v149 offset:1024
	ds_read_b128 v[162:165], v149 offset:2048
	ds_read_b128 v[166:169], v149 offset:3072
	ds_read_b128 v[170:173], v150
	ds_read_b128 v[174:177], v150 offset:1024
	ds_read_b128 v[178:181], v150 offset:2048
	ds_read_b128 v[182:185], v150 offset:3072
	ds_read_b128 v[186:189], v151
	ds_read_b128 v[190:193], v151 offset:1024
	ds_read_b128 v[194:197], v151 offset:2048
	ds_read_b128 v[198:201], v151 offset:3072
	ds_read_b128 v[202:205], v151 offset:4096
	ds_read_b128 v[206:209], v151 offset:5120
	ds_read_b128 v[210:213], v151 offset:6144
	ds_read_b128 v[214:217], v151 offset:7168
	s_waitcnt vmcnt(8)
	s_waitcnt lgkmcnt(0)
	s_setprio 1
	s_barrier
	v_mfma_f32_16x16x32_bf16 v[116:119], v[154:157], v[186:189], v[116:119]
	v_mfma_f32_16x16x32_bf16 v[112:115], v[162:165], v[186:189], v[112:115]
	v_mfma_f32_16x16x32_bf16 v[108:111], v[154:157], v[194:197], v[108:111]
	v_mfma_f32_16x16x32_bf16 v[100:103], v[162:165], v[194:197], v[100:103]
	v_mfma_f32_16x16x32_bf16 v[92:95], v[154:157], v[202:205], v[92:95]
	v_mfma_f32_16x16x32_bf16 v[84:87], v[162:165], v[202:205], v[84:87]
	v_mfma_f32_16x16x32_bf16 v[76:79], v[154:157], v[210:213], v[76:79]
	v_mfma_f32_16x16x32_bf16 v[68:71], v[162:165], v[210:213], v[68:71]
	v_mfma_f32_16x16x32_bf16 v[116:119], v[158:161], v[190:193], v[116:119]
	v_mfma_f32_16x16x32_bf16 v[112:115], v[166:169], v[190:193], v[112:115]
	v_mfma_f32_16x16x32_bf16 v[108:111], v[158:161], v[198:201], v[108:111]
	v_mfma_f32_16x16x32_bf16 v[100:103], v[166:169], v[198:201], v[100:103]
	v_mfma_f32_16x16x32_bf16 v[92:95], v[158:161], v[206:209], v[92:95]
	v_mfma_f32_16x16x32_bf16 v[84:87], v[166:169], v[206:209], v[84:87]
	v_mfma_f32_16x16x32_bf16 v[76:79], v[158:161], v[214:217], v[76:79]
	v_mfma_f32_16x16x32_bf16 v[68:71], v[166:169], v[214:217], v[68:71]
	s_setprio 0
	s_setprio 1
	v_mfma_f32_16x16x32_bf16 v[124:127], v[170:173], v[186:189], v[124:127]
	v_mfma_f32_16x16x32_bf16 v[120:123], v[178:181], v[186:189], v[120:123]
	v_mfma_f32_16x16x32_bf16 v[104:107], v[170:173], v[194:197], v[104:107]
	v_mfma_f32_16x16x32_bf16 v[96:99], v[178:181], v[194:197], v[96:99]
	v_mfma_f32_16x16x32_bf16 v[88:91], v[170:173], v[202:205], v[88:91]
	v_mfma_f32_16x16x32_bf16 v[80:83], v[178:181], v[202:205], v[80:83]
	v_mfma_f32_16x16x32_bf16 v[72:75], v[170:173], v[210:213], v[72:75]
	v_mfma_f32_16x16x32_bf16 v[64:67], v[178:181], v[210:213], v[64:67]
	v_mfma_f32_16x16x32_bf16 v[124:127], v[174:177], v[190:193], v[124:127]
	v_mfma_f32_16x16x32_bf16 v[120:123], v[182:185], v[190:193], v[120:123]
	v_mfma_f32_16x16x32_bf16 v[104:107], v[174:177], v[198:201], v[104:107]
	v_mfma_f32_16x16x32_bf16 v[96:99], v[182:185], v[198:201], v[96:99]
	v_mfma_f32_16x16x32_bf16 v[88:91], v[174:177], v[206:209], v[88:91]
	v_mfma_f32_16x16x32_bf16 v[80:83], v[182:185], v[206:209], v[80:83]
	v_mfma_f32_16x16x32_bf16 v[72:75], v[174:177], v[214:217], v[72:75]
	v_mfma_f32_16x16x32_bf16 v[64:67], v[182:185], v[214:217], v[64:67]
	s_barrier
	s_setprio 0
	s_add_i32 s63, s47, s5
	v_lshl_add_u64 v[144:145], s[30:31], 0, v[132:133]
	s_mov_b32 m0, s63
	s_nop 0
	global_load_lds_dwordx4 v[144:145], off
	s_add_i32 m0, s63, 0x2000
	s_add_u32 s64, s30, 0x40000
	v_lshl_add_u64 v[218:219], s[30:31], 0, v[128:129]
	s_addc_u32 s65, s31, 0
	s_add_i32 s63, s48, s5
	global_load_lds_dwordx4 v[218:219], off
	v_lshl_add_u64 v[220:221], s[64:65], 0, v[132:133]
	s_mov_b32 m0, s63
	v_lshl_add_u64 v[222:223], s[34:35], 0, v[130:131]
	global_load_lds_dwordx4 v[220:221], off
	v_lshl_add_u64 v[220:221], s[64:65], 0, v[128:129]
	s_add_i32 m0, s63, 0x2000
	s_nop 0
	global_load_lds_dwordx4 v[220:221], off
	v_lshl_add_u64 v[220:221], s[34:35], 0, v[134:135]
	s_mov_b32 m0, s25
	s_nop 0
	global_load_lds_dwordx4 v[220:221], off
	s_mov_b32 m0, s27
	s_nop 0
	global_load_lds_dwordx4 v[222:223], off
	ds_read_b128 v[186:189], v151 offset:16384
	ds_read_b128 v[190:193], v151 offset:17408
	ds_read_b128 v[194:197], v151 offset:18432
	ds_read_b128 v[198:201], v151 offset:19456
	ds_read_b128 v[202:205], v151 offset:20480
	ds_read_b128 v[206:209], v151 offset:21504
	ds_read_b128 v[210:213], v151 offset:22528
	ds_read_b128 v[214:217], v151 offset:23552
	s_waitcnt vmcnt(8)
	s_waitcnt lgkmcnt(0)
	s_setprio 1
	s_barrier
	v_mfma_f32_16x16x32_bf16 v[60:63], v[154:157], v[186:189], v[60:63]
	v_mfma_f32_16x16x32_bf16 v[52:55], v[162:165], v[186:189], v[52:55]
	v_mfma_f32_16x16x32_bf16 v[44:47], v[154:157], v[194:197], v[44:47]
	v_mfma_f32_16x16x32_bf16 v[36:39], v[162:165], v[194:197], v[36:39]
	v_mfma_f32_16x16x32_bf16 v[28:31], v[154:157], v[202:205], v[28:31]
	v_mfma_f32_16x16x32_bf16 v[20:23], v[162:165], v[202:205], v[20:23]
	v_mfma_f32_16x16x32_bf16 v[12:15], v[154:157], v[210:213], v[12:15]
	v_mfma_f32_16x16x32_bf16 v[4:7], v[162:165], v[210:213], v[4:7]
	v_mfma_f32_16x16x32_bf16 v[60:63], v[158:161], v[190:193], v[60:63]
	v_mfma_f32_16x16x32_bf16 v[52:55], v[166:169], v[190:193], v[52:55]
	v_mfma_f32_16x16x32_bf16 v[44:47], v[158:161], v[198:201], v[44:47]
	v_mfma_f32_16x16x32_bf16 v[36:39], v[166:169], v[198:201], v[36:39]
	v_mfma_f32_16x16x32_bf16 v[28:31], v[158:161], v[206:209], v[28:31]
	v_mfma_f32_16x16x32_bf16 v[20:23], v[166:169], v[206:209], v[20:23]
	v_mfma_f32_16x16x32_bf16 v[12:15], v[158:161], v[214:217], v[12:15]
	v_mfma_f32_16x16x32_bf16 v[4:7], v[166:169], v[214:217], v[4:7]
	s_setprio 0
	s_setprio 1
	v_mfma_f32_16x16x32_bf16 v[56:59], v[170:173], v[186:189], v[56:59]
	v_mfma_f32_16x16x32_bf16 v[48:51], v[178:181], v[186:189], v[48:51]
	v_mfma_f32_16x16x32_bf16 v[40:43], v[170:173], v[194:197], v[40:43]
	v_mfma_f32_16x16x32_bf16 v[32:35], v[178:181], v[194:197], v[32:35]
	v_mfma_f32_16x16x32_bf16 v[24:27], v[170:173], v[202:205], v[24:27]
	v_mfma_f32_16x16x32_bf16 v[16:19], v[178:181], v[202:205], v[16:19]
	v_mfma_f32_16x16x32_bf16 v[8:11], v[170:173], v[210:213], v[8:11]
	v_mfma_f32_16x16x32_bf16 v[0:3], v[178:181], v[210:213], v[0:3]
	v_mfma_f32_16x16x32_bf16 v[56:59], v[174:177], v[190:193], v[56:59]
	v_mfma_f32_16x16x32_bf16 v[48:51], v[182:185], v[190:193], v[48:51]
	v_mfma_f32_16x16x32_bf16 v[40:43], v[174:177], v[198:201], v[40:43]
	v_mfma_f32_16x16x32_bf16 v[32:35], v[182:185], v[198:201], v[32:35]
	v_mfma_f32_16x16x32_bf16 v[24:27], v[174:177], v[206:209], v[24:27]
	v_mfma_f32_16x16x32_bf16 v[16:19], v[182:185], v[206:209], v[16:19]
	v_mfma_f32_16x16x32_bf16 v[8:11], v[174:177], v[214:217], v[8:11]
	v_mfma_f32_16x16x32_bf16 v[0:3], v[182:185], v[214:217], v[0:3]
	s_barrier
	s_setprio 0
	s_add_i32 s63, 0, 0x18000
	s_add_i32 s64, 0, 0x1c000
	s_add_u32 s34, s34, 0x40000
	s_addc_u32 s35, s35, 0
	s_mov_b32 m0, s38
	v_lshl_add_u64 v[224:225], s[34:35], 0, v[134:135]
	global_load_lds_dwordx4 v[224:225], off
	v_lshl_add_u64 v[224:225], s[34:35], 0, v[130:131]
	s_mov_b32 m0, s39
	s_nop 0
	global_load_lds_dwordx4 v[224:225], off
	v_add_u32_e32 v153, s63, v147
	ds_read_b128 v[154:157], v153
	ds_read_b128 v[158:161], v153 offset:1024
	ds_read_b128 v[162:165], v153 offset:2048
	ds_read_b128 v[166:169], v153 offset:3072
	v_add_u32_e32 v153, s64, v147
	ds_read_b128 v[170:173], v153
	ds_read_b128 v[174:177], v153 offset:1024
	ds_read_b128 v[178:181], v153 offset:2048
	ds_read_b128 v[182:185], v153 offset:3072
	ds_read_b128 v[186:189], v151 offset:32768
	ds_read_b128 v[190:193], v151 offset:33792
	ds_read_b128 v[194:197], v151 offset:34816
	ds_read_b128 v[198:201], v151 offset:35840
	ds_read_b128 v[202:205], v151 offset:36864
	ds_read_b128 v[206:209], v151 offset:37888
	ds_read_b128 v[210:213], v151 offset:38912
	ds_read_b128 v[214:217], v151 offset:39936
	s_waitcnt vmcnt(8)
	s_waitcnt lgkmcnt(0)
	s_setprio 1
	s_barrier
	v_mfma_f32_16x16x32_bf16 v[116:119], v[154:157], v[186:189], v[116:119]
	v_mfma_f32_16x16x32_bf16 v[112:115], v[162:165], v[186:189], v[112:115]
	v_mfma_f32_16x16x32_bf16 v[108:111], v[154:157], v[194:197], v[108:111]
	v_mfma_f32_16x16x32_bf16 v[100:103], v[162:165], v[194:197], v[100:103]
	v_mfma_f32_16x16x32_bf16 v[92:95], v[154:157], v[202:205], v[92:95]
	v_mfma_f32_16x16x32_bf16 v[84:87], v[162:165], v[202:205], v[84:87]
	v_mfma_f32_16x16x32_bf16 v[76:79], v[154:157], v[210:213], v[76:79]
	v_mfma_f32_16x16x32_bf16 v[68:71], v[162:165], v[210:213], v[68:71]
	v_mfma_f32_16x16x32_bf16 v[116:119], v[158:161], v[190:193], v[116:119]
	v_mfma_f32_16x16x32_bf16 v[112:115], v[166:169], v[190:193], v[112:115]
	v_mfma_f32_16x16x32_bf16 v[108:111], v[158:161], v[198:201], v[108:111]
	v_mfma_f32_16x16x32_bf16 v[100:103], v[166:169], v[198:201], v[100:103]
	v_mfma_f32_16x16x32_bf16 v[92:95], v[158:161], v[206:209], v[92:95]
	v_mfma_f32_16x16x32_bf16 v[84:87], v[166:169], v[206:209], v[84:87]
	v_mfma_f32_16x16x32_bf16 v[76:79], v[158:161], v[214:217], v[76:79]
	v_mfma_f32_16x16x32_bf16 v[68:71], v[166:169], v[214:217], v[68:71]
	s_setprio 0
	s_setprio 1
	v_mfma_f32_16x16x32_bf16 v[124:127], v[170:173], v[186:189], v[124:127]
	v_mfma_f32_16x16x32_bf16 v[120:123], v[178:181], v[186:189], v[120:123]
	v_mfma_f32_16x16x32_bf16 v[104:107], v[170:173], v[194:197], v[104:107]
	v_mfma_f32_16x16x32_bf16 v[96:99], v[178:181], v[194:197], v[96:99]
	v_mfma_f32_16x16x32_bf16 v[88:91], v[170:173], v[202:205], v[88:91]
	v_mfma_f32_16x16x32_bf16 v[80:83], v[178:181], v[202:205], v[80:83]
	v_mfma_f32_16x16x32_bf16 v[72:75], v[170:173], v[210:213], v[72:75]
	v_mfma_f32_16x16x32_bf16 v[64:67], v[178:181], v[210:213], v[64:67]
	v_mfma_f32_16x16x32_bf16 v[124:127], v[174:177], v[190:193], v[124:127]
	v_mfma_f32_16x16x32_bf16 v[120:123], v[182:185], v[190:193], v[120:123]
	v_mfma_f32_16x16x32_bf16 v[104:107], v[174:177], v[198:201], v[104:107]
	v_mfma_f32_16x16x32_bf16 v[96:99], v[182:185], v[198:201], v[96:99]
	v_mfma_f32_16x16x32_bf16 v[88:91], v[174:177], v[206:209], v[88:91]
	v_mfma_f32_16x16x32_bf16 v[80:83], v[182:185], v[206:209], v[80:83]
	v_mfma_f32_16x16x32_bf16 v[72:75], v[174:177], v[214:217], v[72:75]
	v_mfma_f32_16x16x32_bf16 v[64:67], v[182:185], v[214:217], v[64:67]
	s_barrier
	s_setprio 0
	s_add_i32 s34, s63, s5
	v_lshl_add_u64 v[144:145], v[144:145], 0, s[12:13]
	s_mov_b32 m0, s34
	s_nop 0
	global_load_lds_dwordx4 v[144:145], off
	s_add_i32 m0, s34, 0x2000
	s_add_u32 s30, s30, 0x40080
	v_lshl_add_u64 v[144:145], v[218:219], 0, s[12:13]
	s_addc_u32 s31, s31, 0
	s_add_i32 s34, s64, s5
	global_load_lds_dwordx4 v[144:145], off
	v_lshl_add_u64 v[144:145], s[30:31], 0, v[132:133]
	s_mov_b32 m0, s34
	s_nop 0
	global_load_lds_dwordx4 v[144:145], off
	v_lshl_add_u64 v[144:145], s[30:31], 0, v[128:129]
	s_add_i32 m0, s34, 0x2000
	s_nop 0
	global_load_lds_dwordx4 v[144:145], off
	v_lshl_add_u64 v[144:145], v[220:221], 0, s[12:13]
	s_mov_b32 m0, s41
	s_nop 0
	global_load_lds_dwordx4 v[144:145], off
	v_lshl_add_u64 v[144:145], v[222:223], 0, s[12:13]
	s_mov_b32 m0, s42
	s_nop 0
	global_load_lds_dwordx4 v[144:145], off
	ds_read_b128 v[186:189], v151 offset:49152
	ds_read_b128 v[190:193], v151 offset:50176
	ds_read_b128 v[194:197], v151 offset:51200
	ds_read_b128 v[198:201], v151 offset:52224
	ds_read_b128 v[202:205], v151 offset:53248
	ds_read_b128 v[206:209], v151 offset:54272
	ds_read_b128 v[210:213], v151 offset:55296
	ds_read_b128 v[214:217], v151 offset:56320
	s_waitcnt vmcnt(8)
	s_waitcnt lgkmcnt(0)
	s_setprio 1
	s_barrier
	v_mfma_f32_16x16x32_bf16 v[60:63], v[154:157], v[186:189], v[60:63]
	v_mfma_f32_16x16x32_bf16 v[52:55], v[162:165], v[186:189], v[52:55]
	v_mfma_f32_16x16x32_bf16 v[44:47], v[154:157], v[194:197], v[44:47]
	v_mfma_f32_16x16x32_bf16 v[36:39], v[162:165], v[194:197], v[36:39]
	v_mfma_f32_16x16x32_bf16 v[28:31], v[154:157], v[202:205], v[28:31]
	v_mfma_f32_16x16x32_bf16 v[20:23], v[162:165], v[202:205], v[20:23]
	v_mfma_f32_16x16x32_bf16 v[12:15], v[154:157], v[210:213], v[12:15]
	v_mfma_f32_16x16x32_bf16 v[4:7], v[162:165], v[210:213], v[4:7]
	v_mfma_f32_16x16x32_bf16 v[60:63], v[158:161], v[190:193], v[60:63]
	v_mfma_f32_16x16x32_bf16 v[52:55], v[166:169], v[190:193], v[52:55]
	v_mfma_f32_16x16x32_bf16 v[44:47], v[158:161], v[198:201], v[44:47]
	v_mfma_f32_16x16x32_bf16 v[36:39], v[166:169], v[198:201], v[36:39]
	v_mfma_f32_16x16x32_bf16 v[28:31], v[158:161], v[206:209], v[28:31]
	v_mfma_f32_16x16x32_bf16 v[20:23], v[166:169], v[206:209], v[20:23]
	v_mfma_f32_16x16x32_bf16 v[12:15], v[158:161], v[214:217], v[12:15]
	v_mfma_f32_16x16x32_bf16 v[4:7], v[166:169], v[214:217], v[4:7]
	s_setprio 0
	s_setprio 1
	v_mfma_f32_16x16x32_bf16 v[56:59], v[170:173], v[186:189], v[56:59]
	v_mfma_f32_16x16x32_bf16 v[48:51], v[178:181], v[186:189], v[48:51]
	v_mfma_f32_16x16x32_bf16 v[40:43], v[170:173], v[194:197], v[40:43]
	v_mfma_f32_16x16x32_bf16 v[32:35], v[178:181], v[194:197], v[32:35]
	v_mfma_f32_16x16x32_bf16 v[24:27], v[170:173], v[202:205], v[24:27]
	v_mfma_f32_16x16x32_bf16 v[16:19], v[178:181], v[202:205], v[16:19]
	v_mfma_f32_16x16x32_bf16 v[8:11], v[170:173], v[210:213], v[8:11]
	v_mfma_f32_16x16x32_bf16 v[0:3], v[178:181], v[210:213], v[0:3]
	v_mfma_f32_16x16x32_bf16 v[56:59], v[174:177], v[190:193], v[56:59]
	v_mfma_f32_16x16x32_bf16 v[48:51], v[182:185], v[190:193], v[48:51]
	v_mfma_f32_16x16x32_bf16 v[40:43], v[174:177], v[198:201], v[40:43]
	v_mfma_f32_16x16x32_bf16 v[32:35], v[182:185], v[198:201], v[32:35]
	v_mfma_f32_16x16x32_bf16 v[24:27], v[174:177], v[206:209], v[24:27]
	v_mfma_f32_16x16x32_bf16 v[16:19], v[182:185], v[206:209], v[16:19]
	v_mfma_f32_16x16x32_bf16 v[8:11], v[174:177], v[214:217], v[8:11]
	v_mfma_f32_16x16x32_bf16 v[0:3], v[182:185], v[214:217], v[0:3]
	s_barrier
	s_setprio 0
	s_add_i32 s62, s62, 2
	s_add_u32 s28, s28, 0x100
	s_addc_u32 s29, s29, 0
	s_add_u32 s60, s60, 0x100
	s_addc_u32 s61, s61, 0
	s_cmp_gt_u32 s62, 13
	s_cbranch_scc0 .LBB0_1193
	s_and_b64 vcc, exec, s[14:15]
	s_cbranch_vccz .LBB0_1196
	s_barrier

.LBB0_1273:
	s_add_u32 s18, s16, 0x100
	s_addc_u32 s19, s17, 0
	s_cmp_eq_u32 s46, 40
	s_cselect_b32 s23, s5, s19
	s_cselect_b32 s22, s4, s18
	s_cselect_b32 s21, s15, s45
	s_cselect_b32 s20, s14, s44
	v_lshl_add_u64 v[192:193], s[16:17], 0, v[172:173]
	s_add_i32 m0, s26, 0xc000
	s_nop 0
	global_load_lds_dwordx4 v[192:193], off
	v_lshl_add_u64 v[192:193], s[16:17], 0, v[174:175]
	s_add_i32 m0, s26, 0xe000
	s_nop 0
	global_load_lds_dwordx4 v[192:193], off
	ds_read_b128 v[128:131], v197
	ds_read_b128 v[132:135], v197 offset:1024
	ds_read_b128 v[136:139], v197 offset:2048
	ds_read_b128 v[140:143], v197 offset:3072
	ds_read_b128 v[144:147], v198
	ds_read_b128 v[148:151], v198 offset:1024
	ds_read_b128 v[152:155], v198 offset:2048
	ds_read_b128 v[156:159], v198 offset:3072
	ds_read_b128 v[160:163], v199
	ds_read_b128 v[180:183], v199 offset:1024
	ds_read_b128 v[184:187], v199 offset:2048
	ds_read_b128 v[188:191], v199 offset:3072
	ds_read_b128 v[200:203], v199 offset:4096
	ds_read_b128 v[204:207], v199 offset:5120
	ds_read_b128 v[208:211], v199 offset:6144
	ds_read_b128 v[212:215], v199 offset:7168
	s_waitcnt vmcnt(8)
	s_waitcnt lgkmcnt(0)
	s_setprio 1
	s_barrier
	v_mfma_f32_16x16x32_bf16 v[124:127], v[128:131], v[160:163], v[124:127]
	v_mfma_f32_16x16x32_bf16 v[120:123], v[136:139], v[160:163], v[120:123]
	v_mfma_f32_16x16x32_bf16 v[112:115], v[128:131], v[184:187], v[112:115]
	v_mfma_f32_16x16x32_bf16 v[104:107], v[136:139], v[184:187], v[104:107]
	v_mfma_f32_16x16x32_bf16 v[96:99], v[128:131], v[200:203], v[96:99]
	v_mfma_f32_16x16x32_bf16 v[88:91], v[136:139], v[200:203], v[88:91]
	v_mfma_f32_16x16x32_bf16 v[80:83], v[128:131], v[208:211], v[80:83]
	v_mfma_f32_16x16x32_bf16 v[72:75], v[136:139], v[208:211], v[72:75]
	v_mfma_f32_16x16x32_bf16 v[124:127], v[132:135], v[180:183], v[124:127]
	v_mfma_f32_16x16x32_bf16 v[120:123], v[140:143], v[180:183], v[120:123]
	v_mfma_f32_16x16x32_bf16 v[112:115], v[132:135], v[188:191], v[112:115]
	v_mfma_f32_16x16x32_bf16 v[104:107], v[140:143], v[188:191], v[104:107]
	v_mfma_f32_16x16x32_bf16 v[96:99], v[132:135], v[204:207], v[96:99]
	v_mfma_f32_16x16x32_bf16 v[88:91], v[140:143], v[204:207], v[88:91]
	v_mfma_f32_16x16x32_bf16 v[80:83], v[132:135], v[212:215], v[80:83]
	v_mfma_f32_16x16x32_bf16 v[72:75], v[140:143], v[212:215], v[72:75]
	s_setprio 0
	s_setprio 1
	v_mfma_f32_16x16x32_bf16 v[116:119], v[144:147], v[160:163], v[116:119]
	v_mfma_f32_16x16x32_bf16 v[108:111], v[152:155], v[160:163], v[108:111]
	v_mfma_f32_16x16x32_bf16 v[100:103], v[144:147], v[184:187], v[100:103]
	v_mfma_f32_16x16x32_bf16 v[92:95], v[152:155], v[184:187], v[92:95]
	v_mfma_f32_16x16x32_bf16 v[84:87], v[144:147], v[200:203], v[84:87]
	v_mfma_f32_16x16x32_bf16 v[76:79], v[152:155], v[200:203], v[76:79]
	v_mfma_f32_16x16x32_bf16 v[68:71], v[144:147], v[208:211], v[68:71]
	v_mfma_f32_16x16x32_bf16 v[64:67], v[152:155], v[208:211], v[64:67]
	v_mfma_f32_16x16x32_bf16 v[116:119], v[148:151], v[180:183], v[116:119]
	v_mfma_f32_16x16x32_bf16 v[108:111], v[156:159], v[180:183], v[108:111]
	v_mfma_f32_16x16x32_bf16 v[100:103], v[148:151], v[188:191], v[100:103]
	v_mfma_f32_16x16x32_bf16 v[92:95], v[156:159], v[188:191], v[92:95]
	v_mfma_f32_16x16x32_bf16 v[84:87], v[148:151], v[204:207], v[84:87]
	v_mfma_f32_16x16x32_bf16 v[76:79], v[156:159], v[204:207], v[76:79]
	v_mfma_f32_16x16x32_bf16 v[68:71], v[148:151], v[212:215], v[68:71]
	v_mfma_f32_16x16x32_bf16 v[64:67], v[156:159], v[212:215], v[64:67]
	s_barrier
	s_setprio 0
	s_add_i32 s16, s38, s25
	v_lshl_add_u64 v[192:193], s[20:21], 0, v[166:167]
	s_mov_b32 m0, s16
	s_nop 0
	global_load_lds_dwordx4 v[192:193], off
	s_add_i32 m0, s16, 0x2000
	s_add_u32 s16, s20, 0xb0000
	v_lshl_add_u64 v[216:217], s[20:21], 0, v[170:171]
	s_addc_u32 s17, s21, 0
	s_add_i32 s47, s39, s25
	global_load_lds_dwordx4 v[216:217], off
	v_lshl_add_u64 v[218:219], s[16:17], 0, v[166:167]
	s_mov_b32 m0, s47
	v_lshl_add_u64 v[220:221], s[22:23], 0, v[168:169]
	global_load_lds_dwordx4 v[218:219], off
	v_lshl_add_u64 v[218:219], s[16:17], 0, v[170:171]
	s_add_i32 m0, s47, 0x2000
	s_nop 0
	global_load_lds_dwordx4 v[218:219], off
	v_lshl_add_u64 v[218:219], s[22:23], 0, v[164:165]
	s_mov_b32 m0, s26
	s_nop 0
	global_load_lds_dwordx4 v[218:219], off
	s_mov_b32 m0, s27
	s_nop 0
	global_load_lds_dwordx4 v[220:221], off
	ds_read_b128 v[160:163], v199 offset:16384
	ds_read_b128 v[180:183], v199 offset:17408
	ds_read_b128 v[184:187], v199 offset:18432
	ds_read_b128 v[188:191], v199 offset:19456
	ds_read_b128 v[200:203], v199 offset:20480
	ds_read_b128 v[204:207], v199 offset:21504
	ds_read_b128 v[208:211], v199 offset:22528
	ds_read_b128 v[212:215], v199 offset:23552
	s_waitcnt vmcnt(8)
	s_waitcnt lgkmcnt(0)
	s_setprio 1
	s_barrier
	v_mfma_f32_16x16x32_bf16 v[60:63], v[128:131], v[160:163], v[60:63]
	v_mfma_f32_16x16x32_bf16 v[56:59], v[136:139], v[160:163], v[56:59]
	v_mfma_f32_16x16x32_bf16 v[48:51], v[128:131], v[184:187], v[48:51]
	v_mfma_f32_16x16x32_bf16 v[40:43], v[136:139], v[184:187], v[40:43]
	v_mfma_f32_16x16x32_bf16 v[32:35], v[128:131], v[200:203], v[32:35]
	v_mfma_f32_16x16x32_bf16 v[24:27], v[136:139], v[200:203], v[24:27]
	v_mfma_f32_16x16x32_bf16 v[16:19], v[128:131], v[208:211], v[16:19]
	v_mfma_f32_16x16x32_bf16 v[8:11], v[136:139], v[208:211], v[8:11]
	v_mfma_f32_16x16x32_bf16 v[60:63], v[132:135], v[180:183], v[60:63]
	v_mfma_f32_16x16x32_bf16 v[56:59], v[140:143], v[180:183], v[56:59]
	v_mfma_f32_16x16x32_bf16 v[48:51], v[132:135], v[188:191], v[48:51]
	v_mfma_f32_16x16x32_bf16 v[40:43], v[140:143], v[188:191], v[40:43]
	v_mfma_f32_16x16x32_bf16 v[32:35], v[132:135], v[204:207], v[32:35]
	v_mfma_f32_16x16x32_bf16 v[24:27], v[140:143], v[204:207], v[24:27]
	v_mfma_f32_16x16x32_bf16 v[16:19], v[132:135], v[212:215], v[16:19]
	v_mfma_f32_16x16x32_bf16 v[8:11], v[140:143], v[212:215], v[8:11]
	s_setprio 0
	s_setprio 1
	v_mfma_f32_16x16x32_bf16 v[52:55], v[144:147], v[160:163], v[52:55]
	v_mfma_f32_16x16x32_bf16 v[44:47], v[152:155], v[160:163], v[44:47]
	v_mfma_f32_16x16x32_bf16 v[36:39], v[144:147], v[184:187], v[36:39]
	v_mfma_f32_16x16x32_bf16 v[28:31], v[152:155], v[184:187], v[28:31]
	v_mfma_f32_16x16x32_bf16 v[20:23], v[144:147], v[200:203], v[20:23]
	v_mfma_f32_16x16x32_bf16 v[12:15], v[152:155], v[200:203], v[12:15]
	v_mfma_f32_16x16x32_bf16 v[4:7], v[144:147], v[208:211], v[4:7]
	v_mfma_f32_16x16x32_bf16 v[0:3], v[152:155], v[208:211], v[0:3]
	v_mfma_f32_16x16x32_bf16 v[52:55], v[148:151], v[180:183], v[52:55]
	v_mfma_f32_16x16x32_bf16 v[44:47], v[156:159], v[180:183], v[44:47]
	v_mfma_f32_16x16x32_bf16 v[36:39], v[148:151], v[188:191], v[36:39]
	v_mfma_f32_16x16x32_bf16 v[28:31], v[156:159], v[188:191], v[28:31]
	v_mfma_f32_16x16x32_bf16 v[20:23], v[148:151], v[204:207], v[20:23]
	v_mfma_f32_16x16x32_bf16 v[12:15], v[156:159], v[204:207], v[12:15]
	v_mfma_f32_16x16x32_bf16 v[4:7], v[148:151], v[212:215], v[4:7]
	v_mfma_f32_16x16x32_bf16 v[0:3], v[156:159], v[212:215], v[0:3]
	s_barrier
	s_setprio 0
	s_add_i32 s47, 0, 0x18000
	s_add_i32 s48, 0, 0x1c000
	s_add_u32 s16, s22, 0xb0000
	s_addc_u32 s17, s23, 0
	s_mov_b32 m0, s28
	v_lshl_add_u64 v[222:223], s[16:17], 0, v[164:165]
	global_load_lds_dwordx4 v[222:223], off
	v_lshl_add_u64 v[222:223], s[16:17], 0, v[168:169]
	s_mov_b32 m0, s29
	s_nop 0
	global_load_lds_dwordx4 v[222:223], off
	v_add_u32_e32 v140, s47, v196
	v_add_u32_e32 v156, s48, v196
	ds_read_b128 v[128:131], v140
	ds_read_b128 v[132:135], v140 offset:1024
	ds_read_b128 v[136:139], v140 offset:2048
	ds_read_b128 v[140:143], v140 offset:3072
	ds_read_b128 v[144:147], v156
	ds_read_b128 v[148:151], v156 offset:1024
	ds_read_b128 v[152:155], v156 offset:2048
	ds_read_b128 v[156:159], v156 offset:3072
	ds_read_b128 v[160:163], v199 offset:32768
	ds_read_b128 v[180:183], v199 offset:33792
	ds_read_b128 v[184:187], v199 offset:34816
	ds_read_b128 v[188:191], v199 offset:35840
	ds_read_b128 v[200:203], v199 offset:36864
	ds_read_b128 v[204:207], v199 offset:37888
	ds_read_b128 v[208:211], v199 offset:38912
	ds_read_b128 v[212:215], v199 offset:39936
	s_waitcnt vmcnt(8)
	s_waitcnt lgkmcnt(0)
	s_setprio 1
	s_barrier
	v_mfma_f32_16x16x32_bf16 v[124:127], v[128:131], v[160:163], v[124:127]
	v_mfma_f32_16x16x32_bf16 v[120:123], v[136:139], v[160:163], v[120:123]
	v_mfma_f32_16x16x32_bf16 v[112:115], v[128:131], v[184:187], v[112:115]
	v_mfma_f32_16x16x32_bf16 v[104:107], v[136:139], v[184:187], v[104:107]
	v_mfma_f32_16x16x32_bf16 v[96:99], v[128:131], v[200:203], v[96:99]
	v_mfma_f32_16x16x32_bf16 v[88:91], v[136:139], v[200:203], v[88:91]
	v_mfma_f32_16x16x32_bf16 v[80:83], v[128:131], v[208:211], v[80:83]
	v_mfma_f32_16x16x32_bf16 v[72:75], v[136:139], v[208:211], v[72:75]
	v_mfma_f32_16x16x32_bf16 v[124:127], v[132:135], v[180:183], v[124:127]
	v_mfma_f32_16x16x32_bf16 v[120:123], v[140:143], v[180:183], v[120:123]
	v_mfma_f32_16x16x32_bf16 v[112:115], v[132:135], v[188:191], v[112:115]
	v_mfma_f32_16x16x32_bf16 v[104:107], v[140:143], v[188:191], v[104:107]
	v_mfma_f32_16x16x32_bf16 v[96:99], v[132:135], v[204:207], v[96:99]
	v_mfma_f32_16x16x32_bf16 v[88:91], v[140:143], v[204:207], v[88:91]
	v_mfma_f32_16x16x32_bf16 v[80:83], v[132:135], v[212:215], v[80:83]
	v_mfma_f32_16x16x32_bf16 v[72:75], v[140:143], v[212:215], v[72:75]
	s_setprio 0
	s_setprio 1
	v_mfma_f32_16x16x32_bf16 v[116:119], v[144:147], v[160:163], v[116:119]
	v_mfma_f32_16x16x32_bf16 v[108:111], v[152:155], v[160:163], v[108:111]
	v_mfma_f32_16x16x32_bf16 v[100:103], v[144:147], v[184:187], v[100:103]
	v_mfma_f32_16x16x32_bf16 v[92:95], v[152:155], v[184:187], v[92:95]
	v_mfma_f32_16x16x32_bf16 v[84:87], v[144:147], v[200:203], v[84:87]
	v_mfma_f32_16x16x32_bf16 v[76:79], v[152:155], v[200:203], v[76:79]
	v_mfma_f32_16x16x32_bf16 v[68:71], v[144:147], v[208:211], v[68:71]
	v_mfma_f32_16x16x32_bf16 v[64:67], v[152:155], v[208:211], v[64:67]
	v_mfma_f32_16x16x32_bf16 v[116:119], v[148:151], v[180:183], v[116:119]
	v_mfma_f32_16x16x32_bf16 v[108:111], v[156:159], v[180:183], v[108:111]
	v_mfma_f32_16x16x32_bf16 v[100:103], v[148:151], v[188:191], v[100:103]
	v_mfma_f32_16x16x32_bf16 v[92:95], v[156:159], v[188:191], v[92:95]
	v_mfma_f32_16x16x32_bf16 v[84:87], v[148:151], v[204:207], v[84:87]
	v_mfma_f32_16x16x32_bf16 v[76:79], v[156:159], v[204:207], v[76:79]
	v_mfma_f32_16x16x32_bf16 v[68:71], v[148:151], v[212:215], v[68:71]
	v_mfma_f32_16x16x32_bf16 v[64:67], v[156:159], v[212:215], v[64:67]
	s_barrier
	s_setprio 0
	s_add_i32 s16, s47, s25
	v_lshl_add_u64 v[192:193], v[192:193], 0, s[10:11]
	s_mov_b32 m0, s16
	s_nop 0
	global_load_lds_dwordx4 v[192:193], off
	s_add_i32 m0, s16, 0x2000
	s_add_u32 s16, s20, 0xb0080
	v_lshl_add_u64 v[192:193], v[216:217], 0, s[10:11]
	s_addc_u32 s17, s21, 0
	s_add_i32 s20, s48, s25
	global_load_lds_dwordx4 v[192:193], off
	v_lshl_add_u64 v[192:193], s[16:17], 0, v[166:167]
	s_mov_b32 m0, s20
	s_nop 0
	global_load_lds_dwordx4 v[192:193], off
	v_lshl_add_u64 v[192:193], s[16:17], 0, v[170:171]
	s_add_i32 m0, s20, 0x2000
	s_nop 0
	global_load_lds_dwordx4 v[192:193], off
	v_lshl_add_u64 v[192:193], v[218:219], 0, s[10:11]
	s_mov_b32 m0, s35
	s_nop 0
	global_load_lds_dwordx4 v[192:193], off
	v_lshl_add_u64 v[192:193], v[220:221], 0, s[10:11]
	s_mov_b32 m0, s36
	s_nop 0
	global_load_lds_dwordx4 v[192:193], off
	ds_read_b128 v[160:163], v199 offset:49152
	ds_read_b128 v[180:183], v199 offset:50176
	ds_read_b128 v[184:187], v199 offset:51200
	ds_read_b128 v[188:191], v199 offset:52224
	ds_read_b128 v[200:203], v199 offset:53248
	ds_read_b128 v[204:207], v199 offset:54272
	ds_read_b128 v[208:211], v199 offset:55296
	ds_read_b128 v[212:215], v199 offset:56320
	s_waitcnt vmcnt(8)
	s_waitcnt lgkmcnt(0)
	s_setprio 1
	s_barrier
	v_mfma_f32_16x16x32_bf16 v[60:63], v[128:131], v[160:163], v[60:63]
	v_mfma_f32_16x16x32_bf16 v[56:59], v[136:139], v[160:163], v[56:59]
	v_mfma_f32_16x16x32_bf16 v[48:51], v[128:131], v[184:187], v[48:51]
	v_mfma_f32_16x16x32_bf16 v[40:43], v[136:139], v[184:187], v[40:43]
	v_mfma_f32_16x16x32_bf16 v[32:35], v[128:131], v[200:203], v[32:35]
	v_mfma_f32_16x16x32_bf16 v[24:27], v[136:139], v[200:203], v[24:27]
	v_mfma_f32_16x16x32_bf16 v[16:19], v[128:131], v[208:211], v[16:19]
	v_mfma_f32_16x16x32_bf16 v[8:11], v[136:139], v[208:211], v[8:11]
	v_mfma_f32_16x16x32_bf16 v[60:63], v[132:135], v[180:183], v[60:63]
	v_mfma_f32_16x16x32_bf16 v[56:59], v[140:143], v[180:183], v[56:59]
	v_mfma_f32_16x16x32_bf16 v[48:51], v[132:135], v[188:191], v[48:51]
	v_mfma_f32_16x16x32_bf16 v[40:43], v[140:143], v[188:191], v[40:43]
	v_mfma_f32_16x16x32_bf16 v[32:35], v[132:135], v[204:207], v[32:35]
	v_mfma_f32_16x16x32_bf16 v[24:27], v[140:143], v[204:207], v[24:27]
	v_mfma_f32_16x16x32_bf16 v[16:19], v[132:135], v[212:215], v[16:19]
	v_mfma_f32_16x16x32_bf16 v[8:11], v[140:143], v[212:215], v[8:11]
	s_setprio 0
	s_setprio 1
	v_mfma_f32_16x16x32_bf16 v[52:55], v[144:147], v[160:163], v[52:55]
	v_mfma_f32_16x16x32_bf16 v[44:47], v[152:155], v[160:163], v[44:47]
	v_mfma_f32_16x16x32_bf16 v[36:39], v[144:147], v[184:187], v[36:39]
	v_mfma_f32_16x16x32_bf16 v[28:31], v[152:155], v[184:187], v[28:31]
	v_mfma_f32_16x16x32_bf16 v[20:23], v[144:147], v[200:203], v[20:23]
	v_mfma_f32_16x16x32_bf16 v[12:15], v[152:155], v[200:203], v[12:15]
	v_mfma_f32_16x16x32_bf16 v[4:7], v[144:147], v[208:211], v[4:7]
	v_mfma_f32_16x16x32_bf16 v[0:3], v[152:155], v[208:211], v[0:3]
	v_mfma_f32_16x16x32_bf16 v[52:55], v[148:151], v[180:183], v[52:55]
	v_mfma_f32_16x16x32_bf16 v[44:47], v[156:159], v[180:183], v[44:47]
	v_mfma_f32_16x16x32_bf16 v[36:39], v[148:151], v[188:191], v[36:39]
	v_mfma_f32_16x16x32_bf16 v[28:31], v[156:159], v[188:191], v[28:31]
	v_mfma_f32_16x16x32_bf16 v[20:23], v[148:151], v[204:207], v[20:23]
	v_mfma_f32_16x16x32_bf16 v[12:15], v[156:159], v[204:207], v[12:15]
	v_mfma_f32_16x16x32_bf16 v[4:7], v[148:151], v[212:215], v[4:7]
	v_mfma_f32_16x16x32_bf16 v[0:3], v[156:159], v[212:215], v[0:3]
	s_barrier
	s_setprio 0
	s_add_i32 s46, s46, 2
	s_add_u32 s44, s44, 0x100
	s_addc_u32 s45, s45, 0
	s_cmp_gt_u32 s46, 41
	s_mov_b64 s[16:17], s[18:19]
	s_cbranch_scc0 .LBB0_1273
	s_and_b64 vcc, exec, s[12:13]
	s_cbranch_vccz .LBB0_1276
	s_barrier
